# FFN-up epilogue stores with nt hint (G is written once, read next phase)
# baseline (speedup 1.0000x reference)
; __device__ __forceinline__ unsigned pk2(float lo, float hi) { f32x2 v = {lo, hi}; return __builtin_bit_cast(unsigned, __builtin_convertvector(v, bf16v2)); }
; __device__ __forceinline__ float sigmoidf_(float a) { return __builtin_amdgcn_rcpf(1.f + __expf(-a)); }
;   __device__ __forceinline__ void operator()(const Acc& acc, int brow, int bcol, int wr, int wc, int fr, int fq, int nai) const {
;     const int f0 = (bcol >> 1) + 32 * wc + 8 * fq;
;     asm volatile("s_waitcnt vmcnt(14)" ::: "memory");
; #pragma unroll
;     for (int ai = 0; ai < 2; ++ai)
; #pragma unroll
;       for (int m = 0; m < 4; ++m) if (ai < nai) {
;         const int r = brow + 128 * ai + 64 * wr + 16 * m + fr;
;         u32x4 o;
; #pragma unroll
;         for (int bj = 0; bj < 2; ++bj) {
;           const f32x4 a = acc[ai][bj][m][0], b = acc[ai][bj][m][1];
;           const float g0 = a[0] * sigmoidf_(a[0]) * b[0], g1 = a[1] * sigmoidf_(a[1]) * b[1];
;           const float g2 = a[2] * sigmoidf_(a[2]) * b[2], g3 = a[3] * sigmoidf_(a[3]) * b[3];
;           if (bj == 0) { o.x = pk2(g0, g1); o.y = pk2(g2, g3); } else { o.z = pk2(g0, g1); o.w = pk2(g2, g3); }
;         }
;         *(u32x4*)(G + (size_t)r * DFF + f0) = o;
.LBB0_309:
	v_mul_f32_e32 v41, 0xbfb8aa3b, v67
	v_exp_f32_e32 v42, v41
	v_mul_f32_e32 v41, 0xbfb8aa3b, v66
	v_exp_f32_e32 v143, v41
	v_mul_f32_e32 v154, 0xbfb8aa3b, v64
	v_add_f32_e32 v42, 1.0, v42
	v_rcp_f32_e32 v43, v42
	v_add_f32_e32 v42, 1.0, v143
	v_mul_f32_e32 v143, 0xbfb8aa3b, v65
	v_exp_f32_e32 v143, v143
	v_exp_f32_e32 v154, v154
	v_rcp_f32_e32 v42, v42
	v_mul_f32_e32 v160, 0xbfb8aa3b, v59
	v_add_f32_e32 v143, 1.0, v143
	v_rcp_f32_e32 v155, v143
	v_add_f32_e32 v143, 1.0, v154
	v_rcp_f32_e32 v154, v143
	v_pk_mul_f32 v[42:43], v[66:67], v[42:43]
	v_exp_f32_e32 v160, v160
	v_pk_mul_f32 v[42:43], v[62:63], v[42:43]
	v_pk_mul_f32 v[154:155], v[64:65], v[154:155]
	v_mul_f32_e32 v161, 0xbfb8aa3b, v58
	v_pk_mul_f32 v[154:155], v[60:61], v[154:155]
	v_exp_f32_e32 v162, v161
	v_cvt_pk_bf16_f32 v154, v154, v155
	v_mul_f32_e32 v155, 0xbfb8aa3b, v48
	v_exp_f32_e32 v156, v155
	v_mul_f32_e32 v155, 0xbfb8aa3b, v49
	v_exp_f32_e32 v157, v155
	v_cvt_pk_bf16_f32 v155, v42, v43
	v_add_f32_e32 v42, 1.0, v156
	v_mul_f32_e32 v156, 0xbfb8aa3b, v50
	v_add_f32_e32 v43, 1.0, v157
	v_exp_f32_e32 v156, v156
	v_mul_f32_e32 v157, 0xbfb8aa3b, v51
	v_exp_f32_e32 v157, v157
	v_rcp_f32_e32 v42, v42
	v_rcp_f32_e32 v43, v43
	v_add_f32_e32 v156, 1.0, v156
	v_add_f32_e32 v160, 1.0, v160
	v_rcp_f32_e32 v158, v156
	v_add_f32_e32 v156, 1.0, v157
	v_rcp_f32_e32 v161, v160
	v_add_f32_e32 v160, 1.0, v162
	v_mul_f32_e32 v162, 0xbfb8aa3b, v57
	v_rcp_f32_e32 v159, v156
	v_exp_f32_e32 v162, v162
	v_mul_f32_e32 v163, 0xbfb8aa3b, v56
	v_exp_f32_e32 v164, v163
	v_pk_mul_f32 v[42:43], v[48:49], v[42:43]
	v_add_f32_e32 v162, 1.0, v162
	v_pk_mul_f32 v[42:43], v[44:45], v[42:43]
	v_lshl_or_b32 v142, s12, 7, v148
	v_cvt_pk_bf16_f32 v156, v42, v43
	v_pk_mul_f32 v[42:43], v[50:51], v[158:159]
	v_rcp_f32_e32 v160, v160
	v_pk_mul_f32 v[42:43], v[46:47], v[42:43]
	v_rcp_f32_e32 v163, v162
	v_add_f32_e32 v162, 1.0, v164
	v_lshl_add_u32 v41, s14, 8, v144
	v_ashrrev_i32_e32 v143, 31, v142
	v_cvt_pk_bf16_f32 v157, v42, v43
	v_mov_b64_e32 v[42:43], s[10:11]
	v_rcp_f32_e32 v162, v162
	v_mad_i64_i32 v[158:159], s[4:5], v41, s64, v[42:43]
	v_lshlrev_b64 v[142:143], 1, v[142:143]
	v_lshl_add_u64 v[158:159], v[158:159], 0, v[142:143]
	s_waitcnt vmcnt(14)
	global_store_dwordx4 v[158:159], v[154:157], off nt
	s_nop 1
	v_pk_mul_f32 v[154:155], v[58:59], v[160:161]
	v_mul_f32_e32 v160, 0xbfb8aa3b, v39
	v_pk_mul_f32 v[156:157], v[54:55], v[154:155]
	v_pk_mul_f32 v[154:155], v[56:57], v[162:163]
	v_exp_f32_e32 v160, v160
	v_pk_mul_f32 v[154:155], v[52:53], v[154:155]
	v_mul_f32_e32 v161, 0xbfb8aa3b, v38
	v_cvt_pk_bf16_f32 v154, v154, v155
	v_mul_f32_e32 v155, 0xbfb8aa3b, v28
	v_exp_f32_e32 v158, v155
	v_mul_f32_e32 v155, 0xbfb8aa3b, v29
	v_exp_f32_e32 v159, v155
	v_cvt_pk_bf16_f32 v155, v156, v157
	v_add_f32_e32 v156, 1.0, v158
	v_mul_f32_e32 v158, 0xbfb8aa3b, v30
	v_add_f32_e32 v157, 1.0, v159
	v_mul_f32_e32 v159, 0xbfb8aa3b, v31
	v_exp_f32_e32 v158, v158
	v_exp_f32_e32 v159, v159
	v_exp_f32_e32 v162, v161
	v_add_f32_e32 v160, 1.0, v160
	v_add_f32_e32 v158, 1.0, v158
	v_add_f32_e32 v159, 1.0, v159
	v_rcp_f32_e32 v161, v160
	v_add_f32_e32 v160, 1.0, v162
	v_mul_f32_e32 v162, 0xbfb8aa3b, v37
	v_rcp_f32_e32 v156, v156
	v_rcp_f32_e32 v157, v157
	v_rcp_f32_e32 v158, v158
	v_rcp_f32_e32 v159, v159
	v_exp_f32_e32 v162, v162
	v_mul_f32_e32 v163, 0xbfb8aa3b, v36
	v_exp_f32_e32 v164, v163
	v_pk_mul_f32 v[156:157], v[28:29], v[156:157]
	v_pk_mul_f32 v[158:159], v[30:31], v[158:159]
	v_add_f32_e32 v162, 1.0, v162
	v_pk_mul_f32 v[156:157], v[24:25], v[156:157]
	v_pk_mul_f32 v[158:159], v[26:27], v[158:159]
	v_rcp_f32_e32 v160, v160
	v_rcp_f32_e32 v163, v162
	v_add_f32_e32 v162, 1.0, v164
	v_cvt_pk_bf16_f32 v156, v156, v157
	v_cvt_pk_bf16_f32 v157, v158, v159
	v_or_b32_e32 v158, 16, v41
	v_rcp_f32_e32 v162, v162
	v_mad_i64_i32 v[158:159], s[4:5], v158, s64, v[42:43]
	v_lshl_add_u64 v[158:159], v[158:159], 0, v[142:143]
	global_store_dwordx4 v[158:159], v[154:157], off nt
	s_nop 1
	v_pk_mul_f32 v[154:155], v[38:39], v[160:161]
	v_mul_f32_e32 v160, 0xbfb8aa3b, v23
	v_pk_mul_f32 v[156:157], v[34:35], v[154:155]
	v_pk_mul_f32 v[154:155], v[36:37], v[162:163]
	v_exp_f32_e32 v160, v160
	v_pk_mul_f32 v[154:155], v[32:33], v[154:155]
	v_mul_f32_e32 v161, 0xbfb8aa3b, v22
	v_cvt_pk_bf16_f32 v154, v154, v155
	v_mul_f32_e32 v155, 0xbfb8aa3b, v16
	v_exp_f32_e32 v158, v155
	v_mul_f32_e32 v155, 0xbfb8aa3b, v17
	v_exp_f32_e32 v159, v155
	v_cvt_pk_bf16_f32 v155, v156, v157
	v_add_f32_e32 v156, 1.0, v158
	v_mul_f32_e32 v158, 0xbfb8aa3b, v18
	v_add_f32_e32 v157, 1.0, v159
	v_mul_f32_e32 v159, 0xbfb8aa3b, v19
	v_exp_f32_e32 v158, v158
	v_exp_f32_e32 v159, v159
	v_exp_f32_e32 v162, v161
	v_add_f32_e32 v160, 1.0, v160
	v_add_f32_e32 v158, 1.0, v158
	v_add_f32_e32 v159, 1.0, v159
	v_rcp_f32_e32 v161, v160
	v_add_f32_e32 v160, 1.0, v162
	v_mul_f32_e32 v162, 0xbfb8aa3b, v21
	v_rcp_f32_e32 v156, v156
	v_rcp_f32_e32 v157, v157
	v_rcp_f32_e32 v158, v158
	v_rcp_f32_e32 v159, v159
	v_exp_f32_e32 v162, v162
	v_mul_f32_e32 v163, 0xbfb8aa3b, v20
	v_exp_f32_e32 v164, v163
	v_pk_mul_f32 v[156:157], v[16:17], v[156:157]
	v_pk_mul_f32 v[158:159], v[18:19], v[158:159]
	v_add_f32_e32 v162, 1.0, v162
	v_pk_mul_f32 v[156:157], v[12:13], v[156:157]
	v_pk_mul_f32 v[158:159], v[14:15], v[158:159]
	v_rcp_f32_e32 v160, v160
	v_rcp_f32_e32 v163, v162
	v_add_f32_e32 v162, 1.0, v164
	v_cvt_pk_bf16_f32 v156, v156, v157
	v_cvt_pk_bf16_f32 v157, v158, v159
	v_or_b32_e32 v158, 32, v41
	v_rcp_f32_e32 v162, v162
	v_mad_i64_i32 v[158:159], s[4:5], v158, s64, v[42:43]
	v_lshl_add_u64 v[158:159], v[158:159], 0, v[142:143]
	global_store_dwordx4 v[158:159], v[154:157], off nt
; __device__ __forceinline__ unsigned pk2(float lo, float hi) { f32x2 v = {lo, hi}; return __builtin_bit_cast(unsigned, __builtin_convertvector(v, bf16v2)); }
; __device__ __forceinline__ float sigmoidf_(float a) { return __builtin_amdgcn_rcpf(1.f + __expf(-a)); }
;   __device__ __forceinline__ void operator()(const Acc& acc, int brow, int bcol, int wr, int wc, int fr, int fq, int nai) const {
;     ...
;     for (int ai = 0; ai < 2; ++ai)
; #pragma unroll
;       for (int m = 0; m < 4; ++m) if (ai < nai) {
;         const int r = brow + 128 * ai + 64 * wr + 16 * m + fr;
;         u32x4 o;
; #pragma unroll
;         for (int bj = 0; bj < 2; ++bj) {
;           const f32x4 a = acc[ai][bj][m][0], b = acc[ai][bj][m][1];
;           const float g0 = a[0] * sigmoidf_(a[0]) * b[0], g1 = a[1] * sigmoidf_(a[1]) * b[1];
;           const float g2 = a[2] * sigmoidf_(a[2]) * b[2], g3 = a[3] * sigmoidf_(a[3]) * b[3];
;           if (bj == 0) { o.x = pk2(g0, g1); o.y = pk2(g2, g3); } else { o.z = pk2(g0, g1); o.w = pk2(g2, g3); }
;         }
;         *(u32x4*)(G + (size_t)r * DFF + f0) = o;
	s_nop 1
	v_pk_mul_f32 v[154:155], v[22:23], v[160:161]
	v_mul_f32_e32 v160, 0xbfb8aa3b, v131
	v_pk_mul_f32 v[156:157], v[10:11], v[154:155]
	v_pk_mul_f32 v[154:155], v[20:21], v[162:163]
	v_exp_f32_e32 v160, v160
	v_pk_mul_f32 v[154:155], v[8:9], v[154:155]
	v_mul_f32_e32 v161, 0xbfb8aa3b, v130
	v_cvt_pk_bf16_f32 v154, v154, v155
	v_mul_f32_e32 v155, 0xbfb8aa3b, v4
	v_exp_f32_e32 v158, v155
	v_mul_f32_e32 v155, 0xbfb8aa3b, v5
	v_exp_f32_e32 v159, v155
	v_cvt_pk_bf16_f32 v155, v156, v157
	v_add_f32_e32 v156, 1.0, v158
	v_mul_f32_e32 v158, 0xbfb8aa3b, v6
	v_add_f32_e32 v157, 1.0, v159
	v_mul_f32_e32 v159, 0xbfb8aa3b, v7
	v_exp_f32_e32 v158, v158
	v_exp_f32_e32 v159, v159
	v_rcp_f32_e32 v156, v156
	v_rcp_f32_e32 v157, v157
	v_add_f32_e32 v158, 1.0, v158
	v_add_f32_e32 v159, 1.0, v159
	v_rcp_f32_e32 v158, v158
	v_rcp_f32_e32 v159, v159
	v_pk_mul_f32 v[156:157], v[4:5], v[156:157]
	v_exp_f32_e32 v161, v161
	v_pk_mul_f32 v[156:157], v[0:1], v[156:157]
	v_pk_mul_f32 v[158:159], v[6:7], v[158:159]
	v_cvt_pk_bf16_f32 v156, v156, v157
	v_pk_mul_f32 v[158:159], v[2:3], v[158:159]
	v_mul_f32_e32 v163, 0xbfb8aa3b, v120
	v_cvt_pk_bf16_f32 v157, v158, v159
	v_or_b32_e32 v158, 48, v41
	v_mad_i64_i32 v[158:159], s[4:5], v158, s64, v[42:43]
	v_lshl_add_u64 v[158:159], v[158:159], 0, v[142:143]
	global_store_dwordx4 v[158:159], v[154:157], off nt
	v_exp_f32_e32 v164, v163
	s_nop 0
	v_mul_f32_e32 v156, 0xbfb8aa3b, v129
	v_exp_f32_e32 v156, v156
	v_mul_f32_e32 v157, 0xbfb8aa3b, v128
	v_exp_f32_e32 v158, v157
	v_add_f32_e32 v154, 1.0, v160
	v_rcp_f32_e32 v155, v154
	v_add_f32_e32 v154, 1.0, v161
	v_add_f32_e32 v156, 1.0, v156
	v_rcp_f32_e32 v154, v154
	v_rcp_f32_e32 v157, v156
	v_add_f32_e32 v156, 1.0, v158
	v_rcp_f32_e32 v156, v156
	v_pk_mul_f32 v[154:155], v[130:131], v[154:155]
	v_add_u32_e32 v160, 0x80, v41
	v_pk_mul_f32 v[158:159], v[126:127], v[154:155]
	v_pk_mul_f32 v[154:155], v[128:129], v[156:157]
	v_mul_f32_e32 v161, 0xbfb8aa3b, v122
	v_pk_mul_f32 v[154:155], v[124:125], v[154:155]
	v_exp_f32_e32 v162, v161
	v_cvt_pk_bf16_f32 v154, v154, v155
	v_mul_f32_e32 v155, 0xbfb8aa3b, v96
	v_exp_f32_e32 v156, v155
	v_mul_f32_e32 v155, 0xbfb8aa3b, v97
	v_exp_f32_e32 v157, v155
	v_cvt_pk_bf16_f32 v155, v158, v159
	v_mul_f32_e32 v158, 0xbfb8aa3b, v98
	v_mul_f32_e32 v159, 0xbfb8aa3b, v99
	v_exp_f32_e32 v158, v158
	v_exp_f32_e32 v159, v159
	v_add_f32_e32 v156, 1.0, v156
	v_add_f32_e32 v157, 1.0, v157
	v_add_f32_e32 v158, 1.0, v158
	v_add_f32_e32 v159, 1.0, v159
	v_rcp_f32_e32 v156, v156
	v_rcp_f32_e32 v157, v157
	v_rcp_f32_e32 v158, v158
	v_rcp_f32_e32 v159, v159
	v_pk_mul_f32 v[156:157], v[96:97], v[156:157]
	s_nop 0
	v_pk_mul_f32 v[156:157], v[92:93], v[156:157]
	v_pk_mul_f32 v[158:159], v[98:99], v[158:159]
	v_cvt_pk_bf16_f32 v156, v156, v157
	v_pk_mul_f32 v[158:159], v[94:95], v[158:159]
	s_nop 0
	v_cvt_pk_bf16_f32 v157, v158, v159
	v_mad_i64_i32 v[158:159], s[4:5], v160, s64, v[42:43]
	v_mul_f32_e32 v160, 0xbfb8aa3b, v123
	v_exp_f32_e32 v160, v160
	v_lshl_add_u64 v[158:159], v[158:159], 0, v[142:143]
	global_store_dwordx4 v[158:159], v[154:157], off nt
	v_add_f32_e32 v160, 1.0, v160
	v_rcp_f32_e32 v161, v160
	v_add_f32_e32 v160, 1.0, v162
	v_mul_f32_e32 v162, 0xbfb8aa3b, v121
	v_exp_f32_e32 v162, v162
	v_rcp_f32_e32 v160, v160
	v_add_f32_e32 v162, 1.0, v162
	v_rcp_f32_e32 v163, v162
	v_add_f32_e32 v162, 1.0, v164
	v_rcp_f32_e32 v162, v162
	v_pk_mul_f32 v[154:155], v[122:123], v[160:161]
	v_mul_f32_e32 v160, 0xbfb8aa3b, v115
	v_pk_mul_f32 v[156:157], v[118:119], v[154:155]
	v_pk_mul_f32 v[154:155], v[120:121], v[162:163]
	v_exp_f32_e32 v160, v160
	v_pk_mul_f32 v[154:155], v[116:117], v[154:155]
	v_mul_f32_e32 v161, 0xbfb8aa3b, v114
	v_cvt_pk_bf16_f32 v154, v154, v155
	v_mul_f32_e32 v155, 0xbfb8aa3b, v88
	v_exp_f32_e32 v158, v155
	v_mul_f32_e32 v155, 0xbfb8aa3b, v89
	v_exp_f32_e32 v159, v155
	v_cvt_pk_bf16_f32 v155, v156, v157
	v_add_f32_e32 v156, 1.0, v158
	v_mul_f32_e32 v158, 0xbfb8aa3b, v90
	v_add_f32_e32 v157, 1.0, v159
	v_mul_f32_e32 v159, 0xbfb8aa3b, v91
	v_exp_f32_e32 v158, v158
; __device__ __forceinline__ unsigned pk2(float lo, float hi) { f32x2 v = {lo, hi}; return __builtin_bit_cast(unsigned, __builtin_convertvector(v, bf16v2)); }
; __device__ __forceinline__ float sigmoidf_(float a) { return __builtin_amdgcn_rcpf(1.f + __expf(-a)); }
;   __device__ __forceinline__ void operator()(const Acc& acc, int brow, int bcol, int wr, int wc, int fr, int fq, int nai) const {
;     ...
;     for (int ai = 0; ai < 2; ++ai)
; #pragma unroll
;       for (int m = 0; m < 4; ++m) if (ai < nai) {
;         const int r = brow + 128 * ai + 64 * wr + 16 * m + fr;
;         u32x4 o;
; #pragma unroll
;         for (int bj = 0; bj < 2; ++bj) {
;           const f32x4 a = acc[ai][bj][m][0], b = acc[ai][bj][m][1];
;           const float g0 = a[0] * sigmoidf_(a[0]) * b[0], g1 = a[1] * sigmoidf_(a[1]) * b[1];
;           const float g2 = a[2] * sigmoidf_(a[2]) * b[2], g3 = a[3] * sigmoidf_(a[3]) * b[3];
;           if (bj == 0) { o.x = pk2(g0, g1); o.y = pk2(g2, g3); } else { o.z = pk2(g0, g1); o.w = pk2(g2, g3); }
;         }
;         *(u32x4*)(G + (size_t)r * DFF + f0) = o;
	v_exp_f32_e32 v159, v159
	v_exp_f32_e32 v162, v161
	v_add_f32_e32 v160, 1.0, v160
	v_add_f32_e32 v158, 1.0, v158
	v_add_f32_e32 v159, 1.0, v159
	v_rcp_f32_e32 v161, v160
	v_add_f32_e32 v160, 1.0, v162
	v_mul_f32_e32 v162, 0xbfb8aa3b, v113
	v_rcp_f32_e32 v156, v156
	v_rcp_f32_e32 v157, v157
	v_rcp_f32_e32 v158, v158
	v_rcp_f32_e32 v159, v159
	v_exp_f32_e32 v162, v162
	v_mul_f32_e32 v163, 0xbfb8aa3b, v112
	v_exp_f32_e32 v164, v163
	v_pk_mul_f32 v[156:157], v[88:89], v[156:157]
	v_pk_mul_f32 v[158:159], v[90:91], v[158:159]
	v_add_f32_e32 v162, 1.0, v162
	v_pk_mul_f32 v[156:157], v[84:85], v[156:157]
	v_pk_mul_f32 v[158:159], v[86:87], v[158:159]
	v_rcp_f32_e32 v160, v160
	v_rcp_f32_e32 v163, v162
	v_add_f32_e32 v162, 1.0, v164
	v_cvt_pk_bf16_f32 v156, v156, v157
	v_cvt_pk_bf16_f32 v157, v158, v159
	v_add_u32_e32 v158, 0x90, v41
	v_rcp_f32_e32 v162, v162
	v_mad_i64_i32 v[158:159], s[4:5], v158, s64, v[42:43]
	v_lshl_add_u64 v[158:159], v[158:159], 0, v[142:143]
	global_store_dwordx4 v[158:159], v[154:157], off nt
	s_nop 1
	v_pk_mul_f32 v[154:155], v[114:115], v[160:161]
	v_mul_f32_e32 v160, 0xbfb8aa3b, v107
	v_pk_mul_f32 v[156:157], v[110:111], v[154:155]
	v_pk_mul_f32 v[154:155], v[112:113], v[162:163]
	v_exp_f32_e32 v160, v160
	v_pk_mul_f32 v[154:155], v[108:109], v[154:155]
	v_mul_f32_e32 v161, 0xbfb8aa3b, v106
	v_cvt_pk_bf16_f32 v154, v154, v155
	v_mul_f32_e32 v155, 0xbfb8aa3b, v80
	v_exp_f32_e32 v158, v155
	v_mul_f32_e32 v155, 0xbfb8aa3b, v81
	v_exp_f32_e32 v159, v155
	v_cvt_pk_bf16_f32 v155, v156, v157
	v_add_f32_e32 v156, 1.0, v158
	v_mul_f32_e32 v158, 0xbfb8aa3b, v82
	v_add_f32_e32 v157, 1.0, v159
	v_mul_f32_e32 v159, 0xbfb8aa3b, v83
	v_exp_f32_e32 v158, v158
	v_exp_f32_e32 v159, v159
	v_exp_f32_e32 v162, v161
	v_add_f32_e32 v160, 1.0, v160
	v_add_f32_e32 v158, 1.0, v158
	v_add_f32_e32 v159, 1.0, v159
	v_rcp_f32_e32 v161, v160
	v_add_f32_e32 v160, 1.0, v162
	v_mul_f32_e32 v162, 0xbfb8aa3b, v105
	v_rcp_f32_e32 v156, v156
	v_rcp_f32_e32 v157, v157
	v_rcp_f32_e32 v158, v158
	v_rcp_f32_e32 v159, v159
	v_exp_f32_e32 v162, v162
	v_mul_f32_e32 v163, 0xbfb8aa3b, v104
	v_exp_f32_e32 v164, v163
	v_pk_mul_f32 v[156:157], v[80:81], v[156:157]
	v_pk_mul_f32 v[158:159], v[82:83], v[158:159]
	v_add_f32_e32 v162, 1.0, v162
	v_pk_mul_f32 v[156:157], v[76:77], v[156:157]
	v_pk_mul_f32 v[158:159], v[78:79], v[158:159]
	v_rcp_f32_e32 v160, v160
	v_rcp_f32_e32 v163, v162
	v_add_f32_e32 v162, 1.0, v164
	v_cvt_pk_bf16_f32 v156, v156, v157
	v_cvt_pk_bf16_f32 v157, v158, v159
	v_add_u32_e32 v158, 0xa0, v41
	v_rcp_f32_e32 v162, v162
	v_mad_i64_i32 v[158:159], s[4:5], v158, s64, v[42:43]
	v_lshl_add_u64 v[158:159], v[158:159], 0, v[142:143]
	global_store_dwordx4 v[158:159], v[154:157], off nt
	v_add_u32_e32 v41, 0xb0, v41
	v_mad_i64_i32 v[42:43], s[4:5], v41, s64, v[42:43]
	v_pk_mul_f32 v[154:155], v[106:107], v[160:161]
	v_lshl_add_u64 v[42:43], v[42:43], 0, v[142:143]
	v_pk_mul_f32 v[156:157], v[102:103], v[154:155]
	v_pk_mul_f32 v[154:155], v[104:105], v[162:163]
	s_nop 0
	v_pk_mul_f32 v[154:155], v[100:101], v[154:155]
	s_nop 0
	v_cvt_pk_bf16_f32 v154, v154, v155
	v_mul_f32_e32 v155, 0xbfb8aa3b, v72
	v_exp_f32_e32 v158, v155
	v_mul_f32_e32 v155, 0xbfb8aa3b, v73
	v_exp_f32_e32 v159, v155
	v_cvt_pk_bf16_f32 v155, v156, v157
	v_add_f32_e32 v156, 1.0, v158
	v_mul_f32_e32 v158, 0xbfb8aa3b, v74
	v_add_f32_e32 v157, 1.0, v159
	v_mul_f32_e32 v159, 0xbfb8aa3b, v75
	v_exp_f32_e32 v158, v158
	v_exp_f32_e32 v159, v159
	v_rcp_f32_e32 v156, v156
	v_rcp_f32_e32 v157, v157
	v_add_f32_e32 v158, 1.0, v158
	v_add_f32_e32 v159, 1.0, v159
	v_rcp_f32_e32 v158, v158
	v_rcp_f32_e32 v159, v159
	v_pk_mul_f32 v[156:157], v[72:73], v[156:157]
	v_pk_mul_f32 v[158:159], v[74:75], v[158:159]
	v_pk_mul_f32 v[156:157], v[68:69], v[156:157]
	v_pk_mul_f32 v[158:159], v[70:71], v[158:159]
	v_cvt_pk_bf16_f32 v156, v156, v157
	v_cvt_pk_bf16_f32 v157, v158, v159
	global_store_dwordx4 v[42:43], v[154:157], off nt
	s_add_u32 s0, s0, 0xffffff00
	s_addc_u32 s1, s1, -1
	s_andn2_b64 vcc, exec, s[44:45]
	s_cbranch_vccnz .LBB0_295

.LBB0_314:
	s_add_u32 s0, s18, s8
	ds_read_b128 v[68:71], v149
	ds_read_b128 v[72:75], v149 offset:1024
	ds_read_b128 v[76:79], v149 offset:2048
	ds_read_b128 v[80:83], v149 offset:3072
	s_addc_u32 s1, s19, s9
	s_add_u32 s0, s0, 0x100
	s_addc_u32 s1, s1, 0
	s_add_u32 s4, s20, s8
	s_addc_u32 s5, s21, s9
	s_cmpk_eq_i32 s8, 0x700
	s_cselect_b32 s1, s19, s1
	s_cselect_b32 s0, s18, s0
	s_cselect_b32 s5, s43, s5
	s_cselect_b32 s4, s42, s4
	s_mov_b32 m0, s39
	v_lshl_add_u64 v[116:117], v[42:43], 0, s[8:9]
	ds_read_b128 v[84:87], v150
	ds_read_b128 v[88:91], v150 offset:1024
	ds_read_b128 v[92:95], v150 offset:2048
	ds_read_b128 v[96:99], v150 offset:3072
	ds_read_b128 v[100:103], v150 offset:4096
	ds_read_b128 v[104:107], v150 offset:5120
	ds_read_b128 v[108:111], v150 offset:6144
	ds_read_b128 v[112:115], v150 offset:7168
	global_load_lds_dwordx4 v[116:117], off
	v_lshl_add_u64 v[116:117], v[40:41], 0, s[8:9]
	s_mov_b32 m0, s41
	s_nop 0
	global_load_lds_dwordx4 v[116:117], off
	s_waitcnt lgkmcnt(8)
	s_barrier
	s_waitcnt lgkmcnt(0)
	s_setprio 1
	s_waitcnt lgkmcnt(0)
	v_mfma_f32_16x16x32_bf16 v[64:67], v[68:71], v[84:87], v[64:67]
	v_mfma_f32_16x16x32_bf16 v[60:63], v[76:79], v[84:87], v[60:63]
	v_mfma_f32_16x16x32_bf16 v[56:59], v[68:71], v[92:95], v[56:59]
	v_mfma_f32_16x16x32_bf16 v[52:55], v[76:79], v[92:95], v[52:55]
	v_mfma_f32_16x16x32_bf16 v[36:39], v[68:71], v[100:103], v[36:39]
	v_mfma_f32_16x16x32_bf16 v[32:35], v[76:79], v[100:103], v[32:35]
	v_mfma_f32_16x16x32_bf16 v[20:23], v[68:71], v[108:111], v[20:23]
	v_mfma_f32_16x16x32_bf16 v[8:11], v[76:79], v[108:111], v[8:11]
	v_mfma_f32_16x16x32_bf16 v[64:67], v[72:75], v[88:91], v[64:67]
	v_mfma_f32_16x16x32_bf16 v[60:63], v[80:83], v[88:91], v[60:63]
	v_mfma_f32_16x16x32_bf16 v[56:59], v[72:75], v[96:99], v[56:59]
	v_mfma_f32_16x16x32_bf16 v[52:55], v[80:83], v[96:99], v[52:55]
	v_mfma_f32_16x16x32_bf16 v[36:39], v[72:75], v[104:107], v[36:39]
	v_mfma_f32_16x16x32_bf16 v[32:35], v[80:83], v[104:107], v[32:35]
	v_mfma_f32_16x16x32_bf16 v[20:23], v[72:75], v[112:115], v[20:23]
	v_mfma_f32_16x16x32_bf16 v[8:11], v[80:83], v[112:115], v[8:11]
	s_setprio 0
	s_barrier
	s_mov_b32 m0, s66
	v_lshl_add_u64 v[116:117], s[4:5], 0, v[132:133]
	ds_read_b128 v[68:71], v151
	ds_read_b128 v[72:75], v151 offset:1024
	ds_read_b128 v[76:79], v151 offset:2048
	ds_read_b128 v[80:83], v151 offset:3072
	global_load_lds_dwordx4 v[116:117], off
	v_lshl_add_u64 v[118:119], s[4:5], 0, v[134:135]
	s_mov_b32 m0, s67
	s_nop 0
	global_load_lds_dwordx4 v[118:119], off
	s_barrier
	s_waitcnt lgkmcnt(0)
	s_setprio 1
	s_waitcnt lgkmcnt(0)
	v_mfma_f32_16x16x32_bf16 v[48:51], v[68:71], v[84:87], v[48:51]
	v_mfma_f32_16x16x32_bf16 v[44:47], v[76:79], v[84:87], v[44:47]
	v_mfma_f32_16x16x32_bf16 v[28:31], v[68:71], v[92:95], v[28:31]
	v_mfma_f32_16x16x32_bf16 v[24:27], v[76:79], v[92:95], v[24:27]
	v_mfma_f32_16x16x32_bf16 v[16:19], v[68:71], v[100:103], v[16:19]
	v_mfma_f32_16x16x32_bf16 v[12:15], v[76:79], v[100:103], v[12:15]
	v_mfma_f32_16x16x32_bf16 v[4:7], v[68:71], v[108:111], v[4:7]
	v_mfma_f32_16x16x32_bf16 v[0:3], v[76:79], v[108:111], v[0:3]
	v_mfma_f32_16x16x32_bf16 v[48:51], v[72:75], v[88:91], v[48:51]
	v_mfma_f32_16x16x32_bf16 v[44:47], v[80:83], v[88:91], v[44:47]
	v_mfma_f32_16x16x32_bf16 v[28:31], v[72:75], v[96:99], v[28:31]
	v_mfma_f32_16x16x32_bf16 v[24:27], v[80:83], v[96:99], v[24:27]
	v_mfma_f32_16x16x32_bf16 v[16:19], v[72:75], v[104:107], v[16:19]
	v_mfma_f32_16x16x32_bf16 v[12:15], v[80:83], v[104:107], v[12:15]
	v_mfma_f32_16x16x32_bf16 v[4:7], v[72:75], v[112:115], v[4:7]
	v_mfma_f32_16x16x32_bf16 v[0:3], v[80:83], v[112:115], v[0:3]
	s_setprio 0
	s_mov_b32 m0, s13
	v_lshl_add_u64 v[120:121], s[0:1], 0, v[132:133]
	s_barrier
	global_load_lds_dwordx4 v[120:121], off
	v_lshl_add_u64 v[122:123], s[0:1], 0, v[134:135]
	s_mov_b32 m0, s15
	s_nop 0
	global_load_lds_dwordx4 v[122:123], off
	s_barrier
	s_waitcnt lgkmcnt(0)
	s_barrier
	s_add_u32 s26, s4, 0x40000
	s_addc_u32 s27, s5, 0
	s_mov_b32 m0, s70
	v_lshl_add_u64 v[68:69], s[26:27], 0, v[132:133]
	global_load_lds_dwordx4 v[68:69], off
	v_lshl_add_u64 v[68:69], s[26:27], 0, v[134:135]
	s_mov_b32 m0, s71
	s_nop 0
	global_load_lds_dwordx4 v[68:69], off
	s_waitcnt vmcnt(6)
	s_barrier
	s_barrier
	ds_read_b128 v[68:71], v152
	ds_read_b128 v[72:75], v152 offset:1024
	ds_read_b128 v[76:79], v152 offset:2048
	ds_read_b128 v[80:83], v152 offset:3072
	s_add_u32 s0, s0, s24
	s_addc_u32 s1, s1, s25
	s_mov_b32 m0, s23
	v_lshl_add_u64 v[124:125], s[0:1], 0, v[132:133]
	ds_read_b128 v[84:87], v150 offset:32768
	ds_read_b128 v[88:91], v150 offset:33792
	ds_read_b128 v[92:95], v150 offset:34816
	ds_read_b128 v[96:99], v150 offset:35840
	ds_read_b128 v[100:103], v150 offset:36864
	ds_read_b128 v[104:107], v150 offset:37888
	ds_read_b128 v[108:111], v150 offset:38912
	ds_read_b128 v[112:115], v150 offset:39936
	global_load_lds_dwordx4 v[124:125], off
	v_lshl_add_u64 v[124:125], s[0:1], 0, v[134:135]
	s_mov_b32 m0, s54
	s_nop 0
	global_load_lds_dwordx4 v[124:125], off
	s_waitcnt lgkmcnt(8)
	s_barrier
	s_waitcnt lgkmcnt(0)
	s_setprio 1
	s_waitcnt lgkmcnt(0)
	v_mfma_f32_16x16x32_bf16 v[64:67], v[68:71], v[84:87], v[64:67]
	v_mfma_f32_16x16x32_bf16 v[60:63], v[76:79], v[84:87], v[60:63]
	v_mfma_f32_16x16x32_bf16 v[56:59], v[68:71], v[92:95], v[56:59]
	v_mfma_f32_16x16x32_bf16 v[52:55], v[76:79], v[92:95], v[52:55]
	v_mfma_f32_16x16x32_bf16 v[36:39], v[68:71], v[100:103], v[36:39]
	v_mfma_f32_16x16x32_bf16 v[32:35], v[76:79], v[100:103], v[32:35]
	v_mfma_f32_16x16x32_bf16 v[20:23], v[68:71], v[108:111], v[20:23]
	v_mfma_f32_16x16x32_bf16 v[8:11], v[76:79], v[108:111], v[8:11]
	v_mfma_f32_16x16x32_bf16 v[64:67], v[72:75], v[88:91], v[64:67]
	v_mfma_f32_16x16x32_bf16 v[60:63], v[80:83], v[88:91], v[60:63]
	v_mfma_f32_16x16x32_bf16 v[56:59], v[72:75], v[96:99], v[56:59]
	v_mfma_f32_16x16x32_bf16 v[52:55], v[80:83], v[96:99], v[52:55]
	v_mfma_f32_16x16x32_bf16 v[36:39], v[72:75], v[104:107], v[36:39]
	v_mfma_f32_16x16x32_bf16 v[32:35], v[80:83], v[104:107], v[32:35]
	v_mfma_f32_16x16x32_bf16 v[20:23], v[72:75], v[112:115], v[20:23]
	v_mfma_f32_16x16x32_bf16 v[8:11], v[80:83], v[112:115], v[8:11]
	s_setprio 0
	s_barrier
	s_mov_b32 m0, s2
	v_lshl_add_u64 v[116:117], v[116:117], 0, s[16:17]
	ds_read_b128 v[68:71], v153
	ds_read_b128 v[72:75], v153 offset:1024
	ds_read_b128 v[76:79], v153 offset:2048
	ds_read_b128 v[80:83], v153 offset:3072
	global_load_lds_dwordx4 v[116:117], off
	v_lshl_add_u64 v[116:117], v[118:119], 0, s[16:17]
	s_mov_b32 m0, s3
	s_nop 0
	global_load_lds_dwordx4 v[116:117], off
	s_barrier
	s_waitcnt lgkmcnt(0)
	s_setprio 1
	s_waitcnt lgkmcnt(0)
	v_mfma_f32_16x16x32_bf16 v[48:51], v[68:71], v[84:87], v[48:51]
	v_mfma_f32_16x16x32_bf16 v[44:47], v[76:79], v[84:87], v[44:47]
	v_mfma_f32_16x16x32_bf16 v[28:31], v[68:71], v[92:95], v[28:31]
	v_mfma_f32_16x16x32_bf16 v[24:27], v[76:79], v[92:95], v[24:27]
	v_mfma_f32_16x16x32_bf16 v[16:19], v[68:71], v[100:103], v[16:19]
	v_mfma_f32_16x16x32_bf16 v[12:15], v[76:79], v[100:103], v[12:15]
	v_mfma_f32_16x16x32_bf16 v[4:7], v[68:71], v[108:111], v[4:7]
	v_mfma_f32_16x16x32_bf16 v[0:3], v[76:79], v[108:111], v[0:3]
	v_mfma_f32_16x16x32_bf16 v[48:51], v[72:75], v[88:91], v[48:51]
	v_mfma_f32_16x16x32_bf16 v[44:47], v[80:83], v[88:91], v[44:47]
	v_mfma_f32_16x16x32_bf16 v[28:31], v[72:75], v[96:99], v[28:31]
	v_mfma_f32_16x16x32_bf16 v[24:27], v[80:83], v[96:99], v[24:27]
	v_mfma_f32_16x16x32_bf16 v[16:19], v[72:75], v[104:107], v[16:19]
	v_mfma_f32_16x16x32_bf16 v[12:15], v[80:83], v[104:107], v[12:15]
	v_mfma_f32_16x16x32_bf16 v[4:7], v[72:75], v[112:115], v[4:7]
	v_mfma_f32_16x16x32_bf16 v[0:3], v[80:83], v[112:115], v[0:3]
	s_setprio 0
	s_mov_b32 m0, s57
	v_lshl_add_u64 v[68:69], v[120:121], 0, s[16:17]
	s_barrier
	global_load_lds_dwordx4 v[68:69], off
	v_lshl_add_u64 v[68:69], v[122:123], 0, s[16:17]
	s_mov_b32 m0, s58
	s_nop 0
	global_load_lds_dwordx4 v[68:69], off
	s_barrier
	s_waitcnt lgkmcnt(0)
	s_barrier
	s_add_u32 s0, s4, 0x40080
	s_addc_u32 s1, s5, 0
	s_mov_b32 m0, s50
	v_lshl_add_u64 v[68:69], s[0:1], 0, v[132:133]
	global_load_lds_dwordx4 v[68:69], off
	v_lshl_add_u64 v[68:69], s[0:1], 0, v[134:135]
	s_mov_b32 m0, s51
	s_add_i32 s22, s22, 2
	global_load_lds_dwordx4 v[68:69], off
	s_waitcnt vmcnt(6)
	s_add_u32 s8, s8, 0x100
	s_addc_u32 s9, s9, 0
	s_cmp_gt_u32 s22, 13
	s_barrier
	s_barrier
	s_cbranch_scc0 .LBB0_314
; __device__ __forceinline__ unsigned pk2(float lo, float hi) { f32x2 v = {lo, hi}; return __builtin_bit_cast(unsigned, __builtin_convertvector(v, bf16v2)); }
; __device__ __forceinline__ float sigmoidf_(float a) { return __builtin_amdgcn_rcpf(1.f + __expf(-a)); }
;   __device__ __forceinline__ void operator()(const Acc& acc, int brow, int bcol, int wr, int wc, int fr, int fq, int nai) const {
;     const int f0 = (bcol >> 1) + 32 * wc + 8 * fq;
;     asm volatile("s_waitcnt vmcnt(14)" ::: "memory");
; #pragma unroll
;     for (int ai = 0; ai < 2; ++ai)
; #pragma unroll
;       for (int m = 0; m < 4; ++m) if (ai < nai) {
;         const int r = brow + 128 * ai + 64 * wr + 16 * m + fr;
;         u32x4 o;
; #pragma unroll
;         for (int bj = 0; bj < 2; ++bj) {
;           const f32x4 a = acc[ai][bj][m][0], b = acc[ai][bj][m][1];
;           const float g0 = a[0] * sigmoidf_(a[0]) * b[0], g1 = a[1] * sigmoidf_(a[1]) * b[1];
;           const float g2 = a[2] * sigmoidf_(a[2]) * b[2], g3 = a[3] * sigmoidf_(a[3]) * b[3];
;           if (bj == 0) { o.x = pk2(g0, g1); o.y = pk2(g2, g3); } else { o.z = pk2(g0, g1); o.w = pk2(g2, g3); }
;         }
;         *(u32x4*)(G + (size_t)r * DFF + f0) = o;
;       }
	v_mul_f32_e32 v40, 0xbfb8aa3b, v67
	v_exp_f32_e32 v40, v40
	v_mul_f32_e32 v41, 0xbfb8aa3b, v66
	v_exp_f32_e32 v43, v41
	v_mul_f32_e32 v68, 0xbfb8aa3b, v64
	v_add_f32_e32 v40, 1.0, v40
	v_rcp_f32_e32 v41, v40
	v_add_f32_e32 v40, 1.0, v43
	v_mul_f32_e32 v43, 0xbfb8aa3b, v65
	v_exp_f32_e32 v43, v43
	v_exp_f32_e32 v68, v68
	v_rcp_f32_e32 v40, v40
	s_lshl_b32 s0, s14, 8
	v_add_f32_e32 v43, 1.0, v43
	v_rcp_f32_e32 v69, v43
	v_add_f32_e32 v43, 1.0, v68
	v_rcp_f32_e32 v68, v43
	v_pk_mul_f32 v[40:41], v[66:67], v[40:41]
	s_cmp_gt_i32 s53, 0
	v_pk_mul_f32 v[40:41], v[62:63], v[40:41]
	v_pk_mul_f32 v[62:63], v[64:65], v[68:69]
	s_cselect_b32 s1, 0x80, 0
	v_pk_mul_f32 v[60:61], v[60:61], v[62:63]
	s_lshl_b32 s2, s12, 7
	v_cvt_pk_bf16_f32 v60, v60, v61
	v_mul_f32_e32 v61, 0xbfb8aa3b, v48
	v_exp_f32_e32 v62, v61
	v_mul_f32_e32 v61, 0xbfb8aa3b, v49
	v_exp_f32_e32 v63, v61
	v_cvt_pk_bf16_f32 v61, v40, v41
	v_add_f32_e32 v40, 1.0, v62
	v_mul_f32_e32 v62, 0xbfb8aa3b, v50
	v_add_f32_e32 v41, 1.0, v63
	v_exp_f32_e32 v62, v62
	v_mul_f32_e32 v63, 0xbfb8aa3b, v51
	v_exp_f32_e32 v63, v63
	v_rcp_f32_e32 v40, v40
	v_rcp_f32_e32 v41, v41
	v_add_f32_e32 v62, 1.0, v62
	v_rcp_f32_e32 v64, v62
	v_add_f32_e32 v62, 1.0, v63
	v_rcp_f32_e32 v65, v62
	v_pk_mul_f32 v[40:41], v[48:49], v[40:41]
	v_mul_f32_e32 v49, 0xbfb8aa3b, v56
	v_pk_mul_f32 v[40:41], v[44:45], v[40:41]
	s_or_b32 s2, s2, s56
	v_cvt_pk_bf16_f32 v62, v40, v41
	v_pk_mul_f32 v[40:41], v[50:51], v[64:65]
	v_exp_f32_e32 v50, v49
	v_pk_mul_f32 v[40:41], v[46:47], v[40:41]
	v_mul_f32_e32 v46, 0xbfb8aa3b, v59
	v_exp_f32_e32 v46, v46
	v_mul_f32_e32 v47, 0xbfb8aa3b, v58
	v_exp_f32_e32 v48, v47
	v_or_b32_e32 v42, s2, v145
	v_add_f32_e32 v46, 1.0, v46
	v_rcp_f32_e32 v47, v46
	v_add_f32_e32 v46, 1.0, v48
	v_mul_f32_e32 v48, 0xbfb8aa3b, v57
	v_exp_f32_e32 v48, v48
	s_or_b32 s0, s1, s0
	v_rcp_f32_e32 v46, v46
	v_add_u32_e32 v70, s0, v144
	v_add_f32_e32 v48, 1.0, v48
	v_rcp_f32_e32 v49, v48
	v_add_f32_e32 v48, 1.0, v50
	v_ashrrev_i32_e32 v43, 31, v42
	v_cvt_pk_bf16_f32 v63, v40, v41
	s_movk_i32 s0, 0x1600
	v_mov_b64_e32 v[40:41], s[10:11]
	v_rcp_f32_e32 v48, v48
	v_mad_i64_i32 v[44:45], s[2:3], v70, s0, v[40:41]
	v_lshlrev_b64 v[42:43], 1, v[42:43]
	v_lshl_add_u64 v[44:45], v[44:45], 0, v[42:43]
	s_waitcnt vmcnt(14)
	global_store_dwordx4 v[44:45], v[60:63], off nt
	v_pk_mul_f32 v[44:45], v[58:59], v[46:47]
	s_nop 0
	v_pk_mul_f32 v[46:47], v[54:55], v[44:45]
	v_pk_mul_f32 v[44:45], v[56:57], v[48:49]
	s_nop 0
	v_pk_mul_f32 v[44:45], v[52:53], v[44:45]
	s_nop 0
	v_cvt_pk_bf16_f32 v44, v44, v45
	v_mul_f32_e32 v45, 0xbfb8aa3b, v28
	v_exp_f32_e32 v48, v45
	v_mul_f32_e32 v45, 0xbfb8aa3b, v29
	v_exp_f32_e32 v49, v45
	v_cvt_pk_bf16_f32 v45, v46, v47
	v_add_f32_e32 v46, 1.0, v48
	v_mul_f32_e32 v48, 0xbfb8aa3b, v30
	v_add_f32_e32 v47, 1.0, v49
	v_mul_f32_e32 v49, 0xbfb8aa3b, v31
	v_exp_f32_e32 v48, v48
	v_exp_f32_e32 v49, v49
	v_rcp_f32_e32 v46, v46
	v_rcp_f32_e32 v47, v47
	v_add_f32_e32 v48, 1.0, v48
	v_add_f32_e32 v49, 1.0, v49
	v_rcp_f32_e32 v48, v48
	v_rcp_f32_e32 v49, v49
	v_pk_mul_f32 v[28:29], v[28:29], v[46:47]
	s_nop 0
	v_pk_mul_f32 v[24:25], v[24:25], v[28:29]
	v_mul_f32_e32 v29, 0xbfb8aa3b, v36
	v_cvt_pk_bf16_f32 v46, v24, v25
	v_pk_mul_f32 v[24:25], v[30:31], v[48:49]
	v_exp_f32_e32 v30, v29
	v_pk_mul_f32 v[24:25], v[26:27], v[24:25]
	v_mul_f32_e32 v26, 0xbfb8aa3b, v39
	v_exp_f32_e32 v26, v26
	v_mul_f32_e32 v27, 0xbfb8aa3b, v38
	v_exp_f32_e32 v28, v27
	v_cvt_pk_bf16_f32 v47, v24, v25
	v_add_f32_e32 v26, 1.0, v26
	v_rcp_f32_e32 v27, v26
	v_add_f32_e32 v26, 1.0, v28
	v_mul_f32_e32 v28, 0xbfb8aa3b, v37
	v_exp_f32_e32 v28, v28
	v_rcp_f32_e32 v26, v26
	v_or_b32_e32 v24, 16, v70
	v_mad_i64_i32 v[24:25], s[2:3], v24, s0, v[40:41]
	v_add_f32_e32 v28, 1.0, v28
	v_rcp_f32_e32 v29, v28
	v_add_f32_e32 v28, 1.0, v30
	v_rcp_f32_e32 v28, v28
	v_lshl_add_u64 v[24:25], v[24:25], 0, v[42:43]
	global_store_dwordx4 v[24:25], v[44:47], off nt
	v_pk_mul_f32 v[24:25], v[38:39], v[26:27]
	s_nop 0
	v_pk_mul_f32 v[26:27], v[34:35], v[24:25]
	v_pk_mul_f32 v[24:25], v[36:37], v[28:29]
	s_nop 0
	v_pk_mul_f32 v[24:25], v[32:33], v[24:25]
	s_nop 0
	v_cvt_pk_bf16_f32 v24, v24, v25
	v_mul_f32_e32 v25, 0xbfb8aa3b, v16
	v_exp_f32_e32 v28, v25
	v_mul_f32_e32 v25, 0xbfb8aa3b, v17
	v_exp_f32_e32 v29, v25
	v_cvt_pk_bf16_f32 v25, v26, v27
	v_add_f32_e32 v26, 1.0, v28
	v_mul_f32_e32 v28, 0xbfb8aa3b, v18
	v_add_f32_e32 v27, 1.0, v29
	v_mul_f32_e32 v29, 0xbfb8aa3b, v19
	v_exp_f32_e32 v28, v28
	v_exp_f32_e32 v29, v29
	v_rcp_f32_e32 v26, v26
	v_rcp_f32_e32 v27, v27
	v_add_f32_e32 v28, 1.0, v28
	v_add_f32_e32 v29, 1.0, v29
	v_rcp_f32_e32 v28, v28
	v_rcp_f32_e32 v29, v29
	v_pk_mul_f32 v[16:17], v[16:17], v[26:27]
	s_nop 0
	v_pk_mul_f32 v[12:13], v[12:13], v[16:17]
	v_mul_f32_e32 v17, 0xbfb8aa3b, v20
	v_cvt_pk_bf16_f32 v26, v12, v13
	v_pk_mul_f32 v[12:13], v[18:19], v[28:29]
	v_exp_f32_e32 v18, v17
	v_pk_mul_f32 v[12:13], v[14:15], v[12:13]
	v_mul_f32_e32 v14, 0xbfb8aa3b, v23
	v_exp_f32_e32 v14, v14
	v_mul_f32_e32 v15, 0xbfb8aa3b, v22
	v_exp_f32_e32 v16, v15
	v_cvt_pk_bf16_f32 v27, v12, v13
	v_add_f32_e32 v14, 1.0, v14
	v_rcp_f32_e32 v15, v14
	v_add_f32_e32 v14, 1.0, v16
	v_mul_f32_e32 v16, 0xbfb8aa3b, v21
	v_exp_f32_e32 v16, v16
	v_rcp_f32_e32 v14, v14
	v_or_b32_e32 v12, 32, v70
	v_mad_i64_i32 v[12:13], s[2:3], v12, s0, v[40:41]
	v_add_f32_e32 v16, 1.0, v16
	v_rcp_f32_e32 v17, v16
	v_add_f32_e32 v16, 1.0, v18
	v_rcp_f32_e32 v16, v16
	v_lshl_add_u64 v[12:13], v[12:13], 0, v[42:43]
	global_store_dwordx4 v[12:13], v[24:27], off nt
	v_pk_mul_f32 v[12:13], v[22:23], v[14:15]
	s_nop 0
	v_pk_mul_f32 v[10:11], v[10:11], v[12:13]
	v_pk_mul_f32 v[12:13], v[20:21], v[16:17]
	s_nop 0
	v_pk_mul_f32 v[8:9], v[8:9], v[12:13]
	s_nop 0
	v_cvt_pk_bf16_f32 v8, v8, v9
	v_mul_f32_e32 v9, 0xbfb8aa3b, v4
	v_exp_f32_e32 v12, v9
	v_mul_f32_e32 v9, 0xbfb8aa3b, v5
	v_exp_f32_e32 v13, v9
	v_cvt_pk_bf16_f32 v9, v10, v11
	v_add_f32_e32 v10, 1.0, v12
	v_mul_f32_e32 v12, 0xbfb8aa3b, v6
	v_add_f32_e32 v11, 1.0, v13
	v_mul_f32_e32 v13, 0xbfb8aa3b, v7
	v_exp_f32_e32 v12, v12
	v_exp_f32_e32 v13, v13
	v_rcp_f32_e32 v10, v10
	v_rcp_f32_e32 v11, v11
	v_add_f32_e32 v12, 1.0, v12
	v_add_f32_e32 v13, 1.0, v13
	v_rcp_f32_e32 v12, v12
	v_rcp_f32_e32 v13, v13
	v_pk_mul_f32 v[4:5], v[4:5], v[10:11]
	s_nop 0
	v_pk_mul_f32 v[0:1], v[0:1], v[4:5]
	s_nop 0
	v_cvt_pk_bf16_f32 v10, v0, v1
	v_pk_mul_f32 v[0:1], v[6:7], v[12:13]
	s_nop 0
	v_pk_mul_f32 v[0:1], v[2:3], v[0:1]
	s_nop 0
	v_cvt_pk_bf16_f32 v11, v0, v1
	v_or_b32_e32 v0, 48, v70
	v_mad_i64_i32 v[0:1], s[0:1], v0, s0, v[40:41]
	v_lshl_add_u64 v[0:1], v[0:1], 0, v[42:43]
	global_store_dwordx4 v[0:1], v[8:11], off nt

; __device__ __forceinline__ unsigned pk2(float lo, float hi) { f32x2 v = {lo, hi}; return __builtin_bit_cast(unsigned, __builtin_convertvector(v, bf16v2)); }
; __device__ __forceinline__ float sigmoidf_(float a) { return __builtin_amdgcn_rcpf(1.f + __expf(-a)); }
;   __device__ __forceinline__ void operator()(const Acc& acc, int brow, int bcol, int wr, int wc, int fr, int fq, int nai) const {
;     const int f0 = (bcol >> 1) + 32 * wc + 8 * fq;
;     asm volatile("s_waitcnt vmcnt(14)" ::: "memory");
; #pragma unroll
;     for (int ai = 0; ai < 2; ++ai)
; #pragma unroll
;       for (int m = 0; m < 4; ++m) if (ai < nai) {
;         const int r = brow + 128 * ai + 64 * wr + 16 * m + fr;
;         u32x4 o;
; #pragma unroll
;         for (int bj = 0; bj < 2; ++bj) {
;           const f32x4 a = acc[ai][bj][m][0], b = acc[ai][bj][m][1];
;           const float g0 = a[0] * sigmoidf_(a[0]) * b[0], g1 = a[1] * sigmoidf_(a[1]) * b[1];
;           const float g2 = a[2] * sigmoidf_(a[2]) * b[2], g3 = a[3] * sigmoidf_(a[3]) * b[3];
;           if (bj == 0) { o.x = pk2(g0, g1); o.y = pk2(g2, g3); } else { o.z = pk2(g0, g1); o.w = pk2(g2, g3); }
;         }
;         *(u32x4*)(G + (size_t)r * DFF + f0) = o;
.LBB0_1609:
	v_mul_f32_e32 v49, 0xbfb8aa3b, v67
	v_exp_f32_e32 v50, v49
	v_mul_f32_e32 v49, 0xbfb8aa3b, v66
	v_exp_f32_e32 v143, v49
	v_mul_f32_e32 v154, 0xbfb8aa3b, v64
	v_add_f32_e32 v50, 1.0, v50
	v_rcp_f32_e32 v51, v50
	v_add_f32_e32 v50, 1.0, v143
	v_mul_f32_e32 v143, 0xbfb8aa3b, v65
	v_exp_f32_e32 v143, v143
	v_exp_f32_e32 v154, v154
	v_rcp_f32_e32 v50, v50
	v_mul_f32_e32 v160, 0xbfb8aa3b, v47
	v_add_f32_e32 v143, 1.0, v143
	v_rcp_f32_e32 v155, v143
	v_add_f32_e32 v143, 1.0, v154
	v_rcp_f32_e32 v154, v143
	v_pk_mul_f32 v[50:51], v[66:67], v[50:51]
	v_exp_f32_e32 v160, v160
	v_pk_mul_f32 v[50:51], v[62:63], v[50:51]
	v_pk_mul_f32 v[154:155], v[64:65], v[154:155]
	v_mul_f32_e32 v161, 0xbfb8aa3b, v46
	v_pk_mul_f32 v[154:155], v[60:61], v[154:155]
	v_exp_f32_e32 v162, v161
	v_cvt_pk_bf16_f32 v154, v154, v155
	v_mul_f32_e32 v155, 0xbfb8aa3b, v56
	v_exp_f32_e32 v156, v155
	v_mul_f32_e32 v155, 0xbfb8aa3b, v57
	v_exp_f32_e32 v157, v155
	v_cvt_pk_bf16_f32 v155, v50, v51
	v_add_f32_e32 v50, 1.0, v156
	v_mul_f32_e32 v156, 0xbfb8aa3b, v58
	v_add_f32_e32 v51, 1.0, v157
	v_exp_f32_e32 v156, v156
	v_mul_f32_e32 v157, 0xbfb8aa3b, v59
	v_exp_f32_e32 v157, v157
	v_rcp_f32_e32 v50, v50
	v_rcp_f32_e32 v51, v51
	v_add_f32_e32 v156, 1.0, v156
	v_add_f32_e32 v160, 1.0, v160
	v_rcp_f32_e32 v158, v156
	v_add_f32_e32 v156, 1.0, v157
	v_rcp_f32_e32 v161, v160
	v_add_f32_e32 v160, 1.0, v162
	v_mul_f32_e32 v162, 0xbfb8aa3b, v45
	v_rcp_f32_e32 v159, v156
	v_exp_f32_e32 v162, v162
	v_mul_f32_e32 v163, 0xbfb8aa3b, v44
	v_exp_f32_e32 v164, v163
	v_pk_mul_f32 v[50:51], v[56:57], v[50:51]
	v_add_f32_e32 v162, 1.0, v162
	v_pk_mul_f32 v[50:51], v[52:53], v[50:51]
	v_lshl_or_b32 v142, s12, 7, v148
	v_cvt_pk_bf16_f32 v156, v50, v51
	v_pk_mul_f32 v[50:51], v[58:59], v[158:159]
	v_rcp_f32_e32 v160, v160
	v_pk_mul_f32 v[50:51], v[54:55], v[50:51]
	v_rcp_f32_e32 v163, v162
	v_add_f32_e32 v162, 1.0, v164
	v_lshl_add_u32 v49, s14, 8, v144
	v_ashrrev_i32_e32 v143, 31, v142
	v_cvt_pk_bf16_f32 v157, v50, v51
	v_mov_b64_e32 v[50:51], s[10:11]
	v_rcp_f32_e32 v162, v162
	v_mad_i64_i32 v[158:159], s[4:5], v49, s64, v[50:51]
	v_lshlrev_b64 v[142:143], 1, v[142:143]
	v_lshl_add_u64 v[158:159], v[158:159], 0, v[142:143]
	s_waitcnt vmcnt(14)
	global_store_dwordx4 v[158:159], v[154:157], off nt
	s_nop 1
	v_pk_mul_f32 v[154:155], v[46:47], v[160:161]
	v_mul_f32_e32 v160, 0xbfb8aa3b, v31
	v_pk_mul_f32 v[156:157], v[42:43], v[154:155]
	v_pk_mul_f32 v[154:155], v[44:45], v[162:163]
	v_exp_f32_e32 v160, v160
	v_pk_mul_f32 v[154:155], v[40:41], v[154:155]
	v_mul_f32_e32 v161, 0xbfb8aa3b, v30
	v_cvt_pk_bf16_f32 v154, v154, v155
	v_mul_f32_e32 v155, 0xbfb8aa3b, v36
	v_exp_f32_e32 v158, v155
	v_mul_f32_e32 v155, 0xbfb8aa3b, v37
	v_exp_f32_e32 v159, v155
	v_cvt_pk_bf16_f32 v155, v156, v157
	v_add_f32_e32 v156, 1.0, v158
	v_mul_f32_e32 v158, 0xbfb8aa3b, v38
	v_add_f32_e32 v157, 1.0, v159
	v_mul_f32_e32 v159, 0xbfb8aa3b, v39
	v_exp_f32_e32 v158, v158
	v_exp_f32_e32 v159, v159
	v_exp_f32_e32 v162, v161
	v_add_f32_e32 v160, 1.0, v160
	v_add_f32_e32 v158, 1.0, v158
	v_add_f32_e32 v159, 1.0, v159
	v_rcp_f32_e32 v161, v160
	v_add_f32_e32 v160, 1.0, v162
	v_mul_f32_e32 v162, 0xbfb8aa3b, v29
	v_rcp_f32_e32 v156, v156
	v_rcp_f32_e32 v157, v157
	v_rcp_f32_e32 v158, v158
	v_rcp_f32_e32 v159, v159
	v_exp_f32_e32 v162, v162
	v_mul_f32_e32 v163, 0xbfb8aa3b, v28
	v_exp_f32_e32 v164, v163
	v_pk_mul_f32 v[156:157], v[36:37], v[156:157]
	v_pk_mul_f32 v[158:159], v[38:39], v[158:159]
	v_add_f32_e32 v162, 1.0, v162
	v_pk_mul_f32 v[156:157], v[32:33], v[156:157]
	v_pk_mul_f32 v[158:159], v[34:35], v[158:159]
	v_rcp_f32_e32 v160, v160
	v_rcp_f32_e32 v163, v162
	v_add_f32_e32 v162, 1.0, v164
	v_cvt_pk_bf16_f32 v156, v156, v157
	v_cvt_pk_bf16_f32 v157, v158, v159
	v_or_b32_e32 v158, 16, v49
	v_rcp_f32_e32 v162, v162
	v_mad_i64_i32 v[158:159], s[4:5], v158, s64, v[50:51]
	v_lshl_add_u64 v[158:159], v[158:159], 0, v[142:143]
	global_store_dwordx4 v[158:159], v[154:157], off nt
	s_nop 1
	v_pk_mul_f32 v[154:155], v[30:31], v[160:161]
	v_mul_f32_e32 v160, 0xbfb8aa3b, v15
	v_pk_mul_f32 v[156:157], v[26:27], v[154:155]
	v_pk_mul_f32 v[154:155], v[28:29], v[162:163]
	v_exp_f32_e32 v160, v160
	v_pk_mul_f32 v[154:155], v[24:25], v[154:155]
	v_mul_f32_e32 v161, 0xbfb8aa3b, v14
	v_cvt_pk_bf16_f32 v154, v154, v155
	v_mul_f32_e32 v155, 0xbfb8aa3b, v20
	v_exp_f32_e32 v158, v155
	v_mul_f32_e32 v155, 0xbfb8aa3b, v21
	v_exp_f32_e32 v159, v155
	v_cvt_pk_bf16_f32 v155, v156, v157
	v_add_f32_e32 v156, 1.0, v158
	v_mul_f32_e32 v158, 0xbfb8aa3b, v22
	v_add_f32_e32 v157, 1.0, v159
	v_mul_f32_e32 v159, 0xbfb8aa3b, v23
	v_exp_f32_e32 v158, v158
	v_exp_f32_e32 v159, v159
	v_exp_f32_e32 v162, v161
	v_add_f32_e32 v160, 1.0, v160
	v_add_f32_e32 v158, 1.0, v158
	v_add_f32_e32 v159, 1.0, v159
	v_rcp_f32_e32 v161, v160
	v_add_f32_e32 v160, 1.0, v162
	v_mul_f32_e32 v162, 0xbfb8aa3b, v13
	v_rcp_f32_e32 v156, v156
	v_rcp_f32_e32 v157, v157
	v_rcp_f32_e32 v158, v158
	v_rcp_f32_e32 v159, v159
	v_exp_f32_e32 v162, v162
	v_mul_f32_e32 v163, 0xbfb8aa3b, v12
	v_exp_f32_e32 v164, v163
	v_pk_mul_f32 v[156:157], v[20:21], v[156:157]
	v_pk_mul_f32 v[158:159], v[22:23], v[158:159]
	v_add_f32_e32 v162, 1.0, v162
	v_pk_mul_f32 v[156:157], v[16:17], v[156:157]
	v_pk_mul_f32 v[158:159], v[18:19], v[158:159]
	v_rcp_f32_e32 v160, v160
	v_rcp_f32_e32 v163, v162
	v_add_f32_e32 v162, 1.0, v164
	v_cvt_pk_bf16_f32 v156, v156, v157
	v_cvt_pk_bf16_f32 v157, v158, v159
	v_or_b32_e32 v158, 32, v49
	v_rcp_f32_e32 v162, v162
	v_mad_i64_i32 v[158:159], s[4:5], v158, s64, v[50:51]
	v_lshl_add_u64 v[158:159], v[158:159], 0, v[142:143]
	global_store_dwordx4 v[158:159], v[154:157], off nt
; __device__ __forceinline__ unsigned pk2(float lo, float hi) { f32x2 v = {lo, hi}; return __builtin_bit_cast(unsigned, __builtin_convertvector(v, bf16v2)); }
; __device__ __forceinline__ float sigmoidf_(float a) { return __builtin_amdgcn_rcpf(1.f + __expf(-a)); }
;   __device__ __forceinline__ void operator()(const Acc& acc, int brow, int bcol, int wr, int wc, int fr, int fq, int nai) const {
;     ...
;     for (int ai = 0; ai < 2; ++ai)
; #pragma unroll
;       for (int m = 0; m < 4; ++m) if (ai < nai) {
;         const int r = brow + 128 * ai + 64 * wr + 16 * m + fr;
;         u32x4 o;
; #pragma unroll
;         for (int bj = 0; bj < 2; ++bj) {
;           const f32x4 a = acc[ai][bj][m][0], b = acc[ai][bj][m][1];
;           const float g0 = a[0] * sigmoidf_(a[0]) * b[0], g1 = a[1] * sigmoidf_(a[1]) * b[1];
;           const float g2 = a[2] * sigmoidf_(a[2]) * b[2], g3 = a[3] * sigmoidf_(a[3]) * b[3];
;           if (bj == 0) { o.x = pk2(g0, g1); o.y = pk2(g2, g3); } else { o.z = pk2(g0, g1); o.w = pk2(g2, g3); }
;         }
;         *(u32x4*)(G + (size_t)r * DFF + f0) = o;
	s_nop 1
	v_pk_mul_f32 v[154:155], v[14:15], v[160:161]
	v_mul_f32_e32 v160, 0xbfb8aa3b, v131
	v_pk_mul_f32 v[156:157], v[10:11], v[154:155]
	v_pk_mul_f32 v[154:155], v[12:13], v[162:163]
	v_exp_f32_e32 v160, v160
	v_pk_mul_f32 v[154:155], v[8:9], v[154:155]
	v_mul_f32_e32 v161, 0xbfb8aa3b, v130
	v_cvt_pk_bf16_f32 v154, v154, v155
	v_mul_f32_e32 v155, 0xbfb8aa3b, v4
	v_exp_f32_e32 v158, v155
	v_mul_f32_e32 v155, 0xbfb8aa3b, v5
	v_exp_f32_e32 v159, v155
	v_cvt_pk_bf16_f32 v155, v156, v157
	v_add_f32_e32 v156, 1.0, v158
	v_mul_f32_e32 v158, 0xbfb8aa3b, v6
	v_add_f32_e32 v157, 1.0, v159
	v_mul_f32_e32 v159, 0xbfb8aa3b, v7
	v_exp_f32_e32 v158, v158
	v_exp_f32_e32 v159, v159
	v_rcp_f32_e32 v156, v156
	v_rcp_f32_e32 v157, v157
	v_add_f32_e32 v158, 1.0, v158
	v_add_f32_e32 v159, 1.0, v159
	v_rcp_f32_e32 v158, v158
	v_rcp_f32_e32 v159, v159
	v_pk_mul_f32 v[156:157], v[4:5], v[156:157]
	v_exp_f32_e32 v161, v161
	v_pk_mul_f32 v[156:157], v[0:1], v[156:157]
	v_pk_mul_f32 v[158:159], v[6:7], v[158:159]
	v_cvt_pk_bf16_f32 v156, v156, v157
	v_pk_mul_f32 v[158:159], v[2:3], v[158:159]
	v_mul_f32_e32 v163, 0xbfb8aa3b, v120
	v_cvt_pk_bf16_f32 v157, v158, v159
	v_or_b32_e32 v158, 48, v49
	v_mad_i64_i32 v[158:159], s[4:5], v158, s64, v[50:51]
	v_lshl_add_u64 v[158:159], v[158:159], 0, v[142:143]
	global_store_dwordx4 v[158:159], v[154:157], off nt
	v_exp_f32_e32 v164, v163
	s_nop 0
	v_mul_f32_e32 v156, 0xbfb8aa3b, v129
	v_exp_f32_e32 v156, v156
	v_mul_f32_e32 v157, 0xbfb8aa3b, v128
	v_exp_f32_e32 v158, v157
	v_add_f32_e32 v154, 1.0, v160
	v_rcp_f32_e32 v155, v154
	v_add_f32_e32 v154, 1.0, v161
	v_add_f32_e32 v156, 1.0, v156
	v_rcp_f32_e32 v154, v154
	v_rcp_f32_e32 v157, v156
	v_add_f32_e32 v156, 1.0, v158
	v_rcp_f32_e32 v156, v156
	v_pk_mul_f32 v[154:155], v[130:131], v[154:155]
	v_add_u32_e32 v160, 0x80, v49
	v_pk_mul_f32 v[158:159], v[126:127], v[154:155]
	v_pk_mul_f32 v[154:155], v[128:129], v[156:157]
	v_mul_f32_e32 v161, 0xbfb8aa3b, v122
	v_pk_mul_f32 v[154:155], v[124:125], v[154:155]
	v_exp_f32_e32 v162, v161
	v_cvt_pk_bf16_f32 v154, v154, v155
	v_mul_f32_e32 v155, 0xbfb8aa3b, v96
	v_exp_f32_e32 v156, v155
	v_mul_f32_e32 v155, 0xbfb8aa3b, v97
	v_exp_f32_e32 v157, v155
	v_cvt_pk_bf16_f32 v155, v158, v159
	v_mul_f32_e32 v158, 0xbfb8aa3b, v98
	v_mul_f32_e32 v159, 0xbfb8aa3b, v99
	v_exp_f32_e32 v158, v158
	v_exp_f32_e32 v159, v159
	v_add_f32_e32 v156, 1.0, v156
	v_add_f32_e32 v157, 1.0, v157
	v_add_f32_e32 v158, 1.0, v158
	v_add_f32_e32 v159, 1.0, v159
	v_rcp_f32_e32 v156, v156
	v_rcp_f32_e32 v157, v157
	v_rcp_f32_e32 v158, v158
	v_rcp_f32_e32 v159, v159
	v_pk_mul_f32 v[156:157], v[96:97], v[156:157]
	s_nop 0
	v_pk_mul_f32 v[156:157], v[92:93], v[156:157]
	v_pk_mul_f32 v[158:159], v[98:99], v[158:159]
	v_cvt_pk_bf16_f32 v156, v156, v157
	v_pk_mul_f32 v[158:159], v[94:95], v[158:159]
	s_nop 0
	v_cvt_pk_bf16_f32 v157, v158, v159
	v_mad_i64_i32 v[158:159], s[4:5], v160, s64, v[50:51]
	v_mul_f32_e32 v160, 0xbfb8aa3b, v123
	v_exp_f32_e32 v160, v160
	v_lshl_add_u64 v[158:159], v[158:159], 0, v[142:143]
	global_store_dwordx4 v[158:159], v[154:157], off nt
	v_add_f32_e32 v160, 1.0, v160
	v_rcp_f32_e32 v161, v160
	v_add_f32_e32 v160, 1.0, v162
	v_mul_f32_e32 v162, 0xbfb8aa3b, v121
	v_exp_f32_e32 v162, v162
	v_rcp_f32_e32 v160, v160
	v_add_f32_e32 v162, 1.0, v162
	v_rcp_f32_e32 v163, v162
	v_add_f32_e32 v162, 1.0, v164
	v_rcp_f32_e32 v162, v162
	v_pk_mul_f32 v[154:155], v[122:123], v[160:161]
	v_mul_f32_e32 v160, 0xbfb8aa3b, v115
	v_pk_mul_f32 v[156:157], v[118:119], v[154:155]
	v_pk_mul_f32 v[154:155], v[120:121], v[162:163]
	v_exp_f32_e32 v160, v160
	v_pk_mul_f32 v[154:155], v[116:117], v[154:155]
	v_mul_f32_e32 v161, 0xbfb8aa3b, v114
	v_cvt_pk_bf16_f32 v154, v154, v155
	v_mul_f32_e32 v155, 0xbfb8aa3b, v88
	v_exp_f32_e32 v158, v155
	v_mul_f32_e32 v155, 0xbfb8aa3b, v89
	v_exp_f32_e32 v159, v155
	v_cvt_pk_bf16_f32 v155, v156, v157
	v_add_f32_e32 v156, 1.0, v158
	v_mul_f32_e32 v158, 0xbfb8aa3b, v90
	v_add_f32_e32 v157, 1.0, v159
	v_mul_f32_e32 v159, 0xbfb8aa3b, v91
	v_exp_f32_e32 v158, v158
; __device__ __forceinline__ unsigned pk2(float lo, float hi) { f32x2 v = {lo, hi}; return __builtin_bit_cast(unsigned, __builtin_convertvector(v, bf16v2)); }
; __device__ __forceinline__ float sigmoidf_(float a) { return __builtin_amdgcn_rcpf(1.f + __expf(-a)); }
;   __device__ __forceinline__ void operator()(const Acc& acc, int brow, int bcol, int wr, int wc, int fr, int fq, int nai) const {
;     ...
;     for (int ai = 0; ai < 2; ++ai)
; #pragma unroll
;       for (int m = 0; m < 4; ++m) if (ai < nai) {
;         const int r = brow + 128 * ai + 64 * wr + 16 * m + fr;
;         u32x4 o;
; #pragma unroll
;         for (int bj = 0; bj < 2; ++bj) {
;           const f32x4 a = acc[ai][bj][m][0], b = acc[ai][bj][m][1];
;           const float g0 = a[0] * sigmoidf_(a[0]) * b[0], g1 = a[1] * sigmoidf_(a[1]) * b[1];
;           const float g2 = a[2] * sigmoidf_(a[2]) * b[2], g3 = a[3] * sigmoidf_(a[3]) * b[3];
;           if (bj == 0) { o.x = pk2(g0, g1); o.y = pk2(g2, g3); } else { o.z = pk2(g0, g1); o.w = pk2(g2, g3); }
;         }
;         *(u32x4*)(G + (size_t)r * DFF + f0) = o;
	v_exp_f32_e32 v159, v159
	v_exp_f32_e32 v162, v161
	v_add_f32_e32 v160, 1.0, v160
	v_add_f32_e32 v158, 1.0, v158
	v_add_f32_e32 v159, 1.0, v159
	v_rcp_f32_e32 v161, v160
	v_add_f32_e32 v160, 1.0, v162
	v_mul_f32_e32 v162, 0xbfb8aa3b, v113
	v_rcp_f32_e32 v156, v156
	v_rcp_f32_e32 v157, v157
	v_rcp_f32_e32 v158, v158
	v_rcp_f32_e32 v159, v159
	v_exp_f32_e32 v162, v162
	v_mul_f32_e32 v163, 0xbfb8aa3b, v112
	v_exp_f32_e32 v164, v163
	v_pk_mul_f32 v[156:157], v[88:89], v[156:157]
	v_pk_mul_f32 v[158:159], v[90:91], v[158:159]
	v_add_f32_e32 v162, 1.0, v162
	v_pk_mul_f32 v[156:157], v[84:85], v[156:157]
	v_pk_mul_f32 v[158:159], v[86:87], v[158:159]
	v_rcp_f32_e32 v160, v160
	v_rcp_f32_e32 v163, v162
	v_add_f32_e32 v162, 1.0, v164
	v_cvt_pk_bf16_f32 v156, v156, v157
	v_cvt_pk_bf16_f32 v157, v158, v159
	v_add_u32_e32 v158, 0x90, v49
	v_rcp_f32_e32 v162, v162
	v_mad_i64_i32 v[158:159], s[4:5], v158, s64, v[50:51]
	v_lshl_add_u64 v[158:159], v[158:159], 0, v[142:143]
	global_store_dwordx4 v[158:159], v[154:157], off nt
	s_nop 1
	v_pk_mul_f32 v[154:155], v[114:115], v[160:161]
	v_mul_f32_e32 v160, 0xbfb8aa3b, v107
	v_pk_mul_f32 v[156:157], v[110:111], v[154:155]
	v_pk_mul_f32 v[154:155], v[112:113], v[162:163]
	v_exp_f32_e32 v160, v160
	v_pk_mul_f32 v[154:155], v[108:109], v[154:155]
	v_mul_f32_e32 v161, 0xbfb8aa3b, v106
	v_cvt_pk_bf16_f32 v154, v154, v155
	v_mul_f32_e32 v155, 0xbfb8aa3b, v80
	v_exp_f32_e32 v158, v155
	v_mul_f32_e32 v155, 0xbfb8aa3b, v81
	v_exp_f32_e32 v159, v155
	v_cvt_pk_bf16_f32 v155, v156, v157
	v_add_f32_e32 v156, 1.0, v158
	v_mul_f32_e32 v158, 0xbfb8aa3b, v82
	v_add_f32_e32 v157, 1.0, v159
	v_mul_f32_e32 v159, 0xbfb8aa3b, v83
	v_exp_f32_e32 v158, v158
	v_exp_f32_e32 v159, v159
	v_exp_f32_e32 v162, v161
	v_add_f32_e32 v160, 1.0, v160
	v_add_f32_e32 v158, 1.0, v158
	v_add_f32_e32 v159, 1.0, v159
	v_rcp_f32_e32 v161, v160
	v_add_f32_e32 v160, 1.0, v162
	v_mul_f32_e32 v162, 0xbfb8aa3b, v105
	v_rcp_f32_e32 v156, v156
	v_rcp_f32_e32 v157, v157
	v_rcp_f32_e32 v158, v158
	v_rcp_f32_e32 v159, v159
	v_exp_f32_e32 v162, v162
	v_mul_f32_e32 v163, 0xbfb8aa3b, v104
	v_exp_f32_e32 v164, v163
	v_pk_mul_f32 v[156:157], v[80:81], v[156:157]
	v_pk_mul_f32 v[158:159], v[82:83], v[158:159]
	v_add_f32_e32 v162, 1.0, v162
	v_pk_mul_f32 v[156:157], v[76:77], v[156:157]
	v_pk_mul_f32 v[158:159], v[78:79], v[158:159]
	v_rcp_f32_e32 v160, v160
	v_rcp_f32_e32 v163, v162
	v_add_f32_e32 v162, 1.0, v164
	v_cvt_pk_bf16_f32 v156, v156, v157
	v_cvt_pk_bf16_f32 v157, v158, v159
	v_add_u32_e32 v158, 0xa0, v49
	v_rcp_f32_e32 v162, v162
	v_mad_i64_i32 v[158:159], s[4:5], v158, s64, v[50:51]
	v_lshl_add_u64 v[158:159], v[158:159], 0, v[142:143]
	global_store_dwordx4 v[158:159], v[154:157], off nt
	v_add_u32_e32 v49, 0xb0, v49
	v_mad_i64_i32 v[50:51], s[4:5], v49, s64, v[50:51]
	v_pk_mul_f32 v[154:155], v[106:107], v[160:161]
	v_lshl_add_u64 v[50:51], v[50:51], 0, v[142:143]
	v_pk_mul_f32 v[156:157], v[102:103], v[154:155]
	v_pk_mul_f32 v[154:155], v[104:105], v[162:163]
	s_nop 0
	v_pk_mul_f32 v[154:155], v[100:101], v[154:155]
	s_nop 0
	v_cvt_pk_bf16_f32 v154, v154, v155
	v_mul_f32_e32 v155, 0xbfb8aa3b, v72
	v_exp_f32_e32 v158, v155
	v_mul_f32_e32 v155, 0xbfb8aa3b, v73
	v_exp_f32_e32 v159, v155
	v_cvt_pk_bf16_f32 v155, v156, v157
	v_add_f32_e32 v156, 1.0, v158
	v_mul_f32_e32 v158, 0xbfb8aa3b, v74
	v_add_f32_e32 v157, 1.0, v159
	v_mul_f32_e32 v159, 0xbfb8aa3b, v75
	v_exp_f32_e32 v158, v158
	v_exp_f32_e32 v159, v159
	v_rcp_f32_e32 v156, v156
	v_rcp_f32_e32 v157, v157
	v_add_f32_e32 v158, 1.0, v158
	v_add_f32_e32 v159, 1.0, v159
	v_rcp_f32_e32 v158, v158
	v_rcp_f32_e32 v159, v159
	v_pk_mul_f32 v[156:157], v[72:73], v[156:157]
	v_pk_mul_f32 v[158:159], v[74:75], v[158:159]
	v_pk_mul_f32 v[156:157], v[68:69], v[156:157]
	v_pk_mul_f32 v[158:159], v[70:71], v[158:159]
	v_cvt_pk_bf16_f32 v156, v156, v157
	v_cvt_pk_bf16_f32 v157, v158, v159
	global_store_dwordx4 v[50:51], v[154:157], off nt
	s_add_u32 s0, s0, 0xffffff00
	s_addc_u32 s1, s1, -1
	s_andn2_b64 vcc, exec, s[44:45]
	s_cbranch_vccnz .LBB0_1595

.LBB0_1614:
	s_add_u32 s0, s18, s8
	ds_read_b128 v[68:71], v149
	ds_read_b128 v[72:75], v149 offset:1024
	ds_read_b128 v[76:79], v149 offset:2048
	ds_read_b128 v[80:83], v149 offset:3072
	s_addc_u32 s1, s19, s9
	s_add_u32 s0, s0, 0x100
	s_addc_u32 s1, s1, 0
	s_add_u32 s4, s20, s8
	s_addc_u32 s5, s21, s9
	s_cmpk_eq_i32 s8, 0x700
	s_cselect_b32 s1, s19, s1
	s_cselect_b32 s0, s18, s0
	s_cselect_b32 s5, s43, s5
	s_cselect_b32 s4, s42, s4
	s_mov_b32 m0, s39
	v_lshl_add_u64 v[116:117], v[50:51], 0, s[8:9]
	ds_read_b128 v[84:87], v150
	ds_read_b128 v[88:91], v150 offset:1024
	ds_read_b128 v[92:95], v150 offset:2048
	ds_read_b128 v[96:99], v150 offset:3072
	ds_read_b128 v[100:103], v150 offset:4096
	ds_read_b128 v[104:107], v150 offset:5120
	ds_read_b128 v[108:111], v150 offset:6144
	ds_read_b128 v[112:115], v150 offset:7168
	global_load_lds_dwordx4 v[116:117], off
	v_lshl_add_u64 v[116:117], v[48:49], 0, s[8:9]
	s_mov_b32 m0, s41
	s_nop 0
	global_load_lds_dwordx4 v[116:117], off
	s_waitcnt lgkmcnt(8)
	s_barrier
	s_waitcnt lgkmcnt(0)
	s_setprio 1
	s_waitcnt lgkmcnt(0)
	v_mfma_f32_16x16x32_bf16 v[64:67], v[68:71], v[84:87], v[64:67]
	v_mfma_f32_16x16x32_bf16 v[60:63], v[76:79], v[84:87], v[60:63]
	v_mfma_f32_16x16x32_bf16 v[44:47], v[68:71], v[92:95], v[44:47]
	v_mfma_f32_16x16x32_bf16 v[40:43], v[76:79], v[92:95], v[40:43]
	v_mfma_f32_16x16x32_bf16 v[28:31], v[68:71], v[100:103], v[28:31]
	v_mfma_f32_16x16x32_bf16 v[24:27], v[76:79], v[100:103], v[24:27]
	v_mfma_f32_16x16x32_bf16 v[12:15], v[68:71], v[108:111], v[12:15]
	v_mfma_f32_16x16x32_bf16 v[8:11], v[76:79], v[108:111], v[8:11]
	v_mfma_f32_16x16x32_bf16 v[64:67], v[72:75], v[88:91], v[64:67]
	v_mfma_f32_16x16x32_bf16 v[60:63], v[80:83], v[88:91], v[60:63]
	v_mfma_f32_16x16x32_bf16 v[44:47], v[72:75], v[96:99], v[44:47]
	v_mfma_f32_16x16x32_bf16 v[40:43], v[80:83], v[96:99], v[40:43]
	v_mfma_f32_16x16x32_bf16 v[28:31], v[72:75], v[104:107], v[28:31]
	v_mfma_f32_16x16x32_bf16 v[24:27], v[80:83], v[104:107], v[24:27]
	v_mfma_f32_16x16x32_bf16 v[12:15], v[72:75], v[112:115], v[12:15]
	v_mfma_f32_16x16x32_bf16 v[8:11], v[80:83], v[112:115], v[8:11]
	s_setprio 0
	s_barrier
	s_mov_b32 m0, s66
	v_lshl_add_u64 v[116:117], s[4:5], 0, v[132:133]
	ds_read_b128 v[68:71], v151
	ds_read_b128 v[72:75], v151 offset:1024
	ds_read_b128 v[76:79], v151 offset:2048
	ds_read_b128 v[80:83], v151 offset:3072
	global_load_lds_dwordx4 v[116:117], off
	v_lshl_add_u64 v[118:119], s[4:5], 0, v[134:135]
	s_mov_b32 m0, s67
	s_nop 0
	global_load_lds_dwordx4 v[118:119], off
	s_barrier
	s_waitcnt lgkmcnt(0)
	s_setprio 1
	s_waitcnt lgkmcnt(0)
	v_mfma_f32_16x16x32_bf16 v[56:59], v[68:71], v[84:87], v[56:59]
	v_mfma_f32_16x16x32_bf16 v[52:55], v[76:79], v[84:87], v[52:55]
	v_mfma_f32_16x16x32_bf16 v[36:39], v[68:71], v[92:95], v[36:39]
	v_mfma_f32_16x16x32_bf16 v[32:35], v[76:79], v[92:95], v[32:35]
	v_mfma_f32_16x16x32_bf16 v[20:23], v[68:71], v[100:103], v[20:23]
	v_mfma_f32_16x16x32_bf16 v[16:19], v[76:79], v[100:103], v[16:19]
	v_mfma_f32_16x16x32_bf16 v[4:7], v[68:71], v[108:111], v[4:7]
	v_mfma_f32_16x16x32_bf16 v[0:3], v[76:79], v[108:111], v[0:3]
	v_mfma_f32_16x16x32_bf16 v[56:59], v[72:75], v[88:91], v[56:59]
	v_mfma_f32_16x16x32_bf16 v[52:55], v[80:83], v[88:91], v[52:55]
	v_mfma_f32_16x16x32_bf16 v[36:39], v[72:75], v[96:99], v[36:39]
	v_mfma_f32_16x16x32_bf16 v[32:35], v[80:83], v[96:99], v[32:35]
	v_mfma_f32_16x16x32_bf16 v[20:23], v[72:75], v[104:107], v[20:23]
	v_mfma_f32_16x16x32_bf16 v[16:19], v[80:83], v[104:107], v[16:19]
	v_mfma_f32_16x16x32_bf16 v[4:7], v[72:75], v[112:115], v[4:7]
	v_mfma_f32_16x16x32_bf16 v[0:3], v[80:83], v[112:115], v[0:3]
	s_setprio 0
	s_mov_b32 m0, s13
	v_lshl_add_u64 v[120:121], s[0:1], 0, v[132:133]
	s_barrier
	global_load_lds_dwordx4 v[120:121], off
	v_lshl_add_u64 v[122:123], s[0:1], 0, v[134:135]
	s_mov_b32 m0, s15
	s_nop 0
	global_load_lds_dwordx4 v[122:123], off
	s_barrier
	s_waitcnt lgkmcnt(0)
	s_barrier
	s_add_u32 s26, s4, 0x40000
	s_addc_u32 s27, s5, 0
	s_mov_b32 m0, s70
	v_lshl_add_u64 v[68:69], s[26:27], 0, v[132:133]
	global_load_lds_dwordx4 v[68:69], off
	v_lshl_add_u64 v[68:69], s[26:27], 0, v[134:135]
	s_mov_b32 m0, s71
	s_nop 0
	global_load_lds_dwordx4 v[68:69], off
	s_waitcnt vmcnt(6)
	s_barrier
	s_barrier
	ds_read_b128 v[68:71], v152
	ds_read_b128 v[72:75], v152 offset:1024
	ds_read_b128 v[76:79], v152 offset:2048
	ds_read_b128 v[80:83], v152 offset:3072
	s_add_u32 s0, s0, s24
	s_addc_u32 s1, s1, s25
	s_mov_b32 m0, s23
	v_lshl_add_u64 v[124:125], s[0:1], 0, v[132:133]
	ds_read_b128 v[84:87], v150 offset:32768
	ds_read_b128 v[88:91], v150 offset:33792
	ds_read_b128 v[92:95], v150 offset:34816
	ds_read_b128 v[96:99], v150 offset:35840
	ds_read_b128 v[100:103], v150 offset:36864
	ds_read_b128 v[104:107], v150 offset:37888
	ds_read_b128 v[108:111], v150 offset:38912
	ds_read_b128 v[112:115], v150 offset:39936
	global_load_lds_dwordx4 v[124:125], off
	v_lshl_add_u64 v[124:125], s[0:1], 0, v[134:135]
	s_mov_b32 m0, s54
	s_nop 0
	global_load_lds_dwordx4 v[124:125], off
	s_waitcnt lgkmcnt(8)
	s_barrier
	s_waitcnt lgkmcnt(0)
	s_setprio 1
	s_waitcnt lgkmcnt(0)
	v_mfma_f32_16x16x32_bf16 v[64:67], v[68:71], v[84:87], v[64:67]
	v_mfma_f32_16x16x32_bf16 v[60:63], v[76:79], v[84:87], v[60:63]
	v_mfma_f32_16x16x32_bf16 v[44:47], v[68:71], v[92:95], v[44:47]
	v_mfma_f32_16x16x32_bf16 v[40:43], v[76:79], v[92:95], v[40:43]
	v_mfma_f32_16x16x32_bf16 v[28:31], v[68:71], v[100:103], v[28:31]
	v_mfma_f32_16x16x32_bf16 v[24:27], v[76:79], v[100:103], v[24:27]
	v_mfma_f32_16x16x32_bf16 v[12:15], v[68:71], v[108:111], v[12:15]
	v_mfma_f32_16x16x32_bf16 v[8:11], v[76:79], v[108:111], v[8:11]
	v_mfma_f32_16x16x32_bf16 v[64:67], v[72:75], v[88:91], v[64:67]
	v_mfma_f32_16x16x32_bf16 v[60:63], v[80:83], v[88:91], v[60:63]
	v_mfma_f32_16x16x32_bf16 v[44:47], v[72:75], v[96:99], v[44:47]
	v_mfma_f32_16x16x32_bf16 v[40:43], v[80:83], v[96:99], v[40:43]
	v_mfma_f32_16x16x32_bf16 v[28:31], v[72:75], v[104:107], v[28:31]
	v_mfma_f32_16x16x32_bf16 v[24:27], v[80:83], v[104:107], v[24:27]
	v_mfma_f32_16x16x32_bf16 v[12:15], v[72:75], v[112:115], v[12:15]
	v_mfma_f32_16x16x32_bf16 v[8:11], v[80:83], v[112:115], v[8:11]
	s_setprio 0
	s_barrier
	s_mov_b32 m0, s2
	v_lshl_add_u64 v[116:117], v[116:117], 0, s[16:17]
	ds_read_b128 v[68:71], v153
	ds_read_b128 v[72:75], v153 offset:1024
	ds_read_b128 v[76:79], v153 offset:2048
	ds_read_b128 v[80:83], v153 offset:3072
	global_load_lds_dwordx4 v[116:117], off
	v_lshl_add_u64 v[116:117], v[118:119], 0, s[16:17]
	s_mov_b32 m0, s3
	s_nop 0
	global_load_lds_dwordx4 v[116:117], off
	s_barrier
	s_waitcnt lgkmcnt(0)
	s_setprio 1
	s_waitcnt lgkmcnt(0)
	v_mfma_f32_16x16x32_bf16 v[56:59], v[68:71], v[84:87], v[56:59]
	v_mfma_f32_16x16x32_bf16 v[52:55], v[76:79], v[84:87], v[52:55]
	v_mfma_f32_16x16x32_bf16 v[36:39], v[68:71], v[92:95], v[36:39]
	v_mfma_f32_16x16x32_bf16 v[32:35], v[76:79], v[92:95], v[32:35]
	v_mfma_f32_16x16x32_bf16 v[20:23], v[68:71], v[100:103], v[20:23]
	v_mfma_f32_16x16x32_bf16 v[16:19], v[76:79], v[100:103], v[16:19]
	v_mfma_f32_16x16x32_bf16 v[4:7], v[68:71], v[108:111], v[4:7]
	v_mfma_f32_16x16x32_bf16 v[0:3], v[76:79], v[108:111], v[0:3]
	v_mfma_f32_16x16x32_bf16 v[56:59], v[72:75], v[88:91], v[56:59]
	v_mfma_f32_16x16x32_bf16 v[52:55], v[80:83], v[88:91], v[52:55]
	v_mfma_f32_16x16x32_bf16 v[36:39], v[72:75], v[96:99], v[36:39]
	v_mfma_f32_16x16x32_bf16 v[32:35], v[80:83], v[96:99], v[32:35]
	v_mfma_f32_16x16x32_bf16 v[20:23], v[72:75], v[104:107], v[20:23]
	v_mfma_f32_16x16x32_bf16 v[16:19], v[80:83], v[104:107], v[16:19]
	v_mfma_f32_16x16x32_bf16 v[4:7], v[72:75], v[112:115], v[4:7]
	v_mfma_f32_16x16x32_bf16 v[0:3], v[80:83], v[112:115], v[0:3]
	s_setprio 0
	s_mov_b32 m0, s57
	v_lshl_add_u64 v[68:69], v[120:121], 0, s[16:17]
	s_barrier
	global_load_lds_dwordx4 v[68:69], off
	v_lshl_add_u64 v[68:69], v[122:123], 0, s[16:17]
	s_mov_b32 m0, s58
	s_nop 0
	global_load_lds_dwordx4 v[68:69], off
	s_barrier
	s_waitcnt lgkmcnt(0)
	s_barrier
	s_add_u32 s0, s4, 0x40080
	s_addc_u32 s1, s5, 0
	s_mov_b32 m0, s50
	v_lshl_add_u64 v[68:69], s[0:1], 0, v[132:133]
	global_load_lds_dwordx4 v[68:69], off
	v_lshl_add_u64 v[68:69], s[0:1], 0, v[134:135]
	s_mov_b32 m0, s51
	s_add_i32 s22, s22, 2
	global_load_lds_dwordx4 v[68:69], off
	s_waitcnt vmcnt(6)
	s_add_u32 s8, s8, 0x100
	s_addc_u32 s9, s9, 0
	s_cmp_gt_u32 s22, 13
	s_barrier
	s_barrier
	s_cbranch_scc0 .LBB0_1614
; __device__ __forceinline__ unsigned pk2(float lo, float hi) { f32x2 v = {lo, hi}; return __builtin_bit_cast(unsigned, __builtin_convertvector(v, bf16v2)); }
; __device__ __forceinline__ float sigmoidf_(float a) { return __builtin_amdgcn_rcpf(1.f + __expf(-a)); }
;     ...
;       epi(acc, cpm * BM + (chf > 0 ? HALF : 0), cpn * BM, wr, wc, fr, fq, 1);
;   __device__ __forceinline__ void operator()(const Acc& acc, int brow, int bcol, int wr, int wc, int fr, int fq, int nai) const {
;     const int f0 = (bcol >> 1) + 32 * wc + 8 * fq;
;     asm volatile("s_waitcnt vmcnt(14)" ::: "memory");
; #pragma unroll
;     for (int ai = 0; ai < 2; ++ai)
; #pragma unroll
;       for (int m = 0; m < 4; ++m) if (ai < nai) {
;         const int r = brow + 128 * ai + 64 * wr + 16 * m + fr;
;         u32x4 o;
; #pragma unroll
;         for (int bj = 0; bj < 2; ++bj) {
;           const f32x4 a = acc[ai][bj][m][0], b = acc[ai][bj][m][1];
;           const float g0 = a[0] * sigmoidf_(a[0]) * b[0], g1 = a[1] * sigmoidf_(a[1]) * b[1];
;           const float g2 = a[2] * sigmoidf_(a[2]) * b[2], g3 = a[3] * sigmoidf_(a[3]) * b[3];
;           if (bj == 0) { o.x = pk2(g0, g1); o.y = pk2(g2, g3); } else { o.z = pk2(g0, g1); o.w = pk2(g2, g3); }
;         }
;         *(u32x4*)(G + (size_t)r * DFF + f0) = o;
;       }
	v_mul_f32_e32 v48, 0xbfb8aa3b, v67
	v_exp_f32_e32 v48, v48
	v_mul_f32_e32 v49, 0xbfb8aa3b, v66
	v_exp_f32_e32 v51, v49
	v_mul_f32_e32 v68, 0xbfb8aa3b, v64
	v_add_f32_e32 v48, 1.0, v48
	v_rcp_f32_e32 v49, v48
	v_add_f32_e32 v48, 1.0, v51
	v_mul_f32_e32 v51, 0xbfb8aa3b, v65
	v_exp_f32_e32 v51, v51
	v_exp_f32_e32 v68, v68
	v_rcp_f32_e32 v48, v48
	s_lshl_b32 s0, s14, 8
	v_add_f32_e32 v51, 1.0, v51
	v_rcp_f32_e32 v69, v51
	v_add_f32_e32 v51, 1.0, v68
	v_rcp_f32_e32 v68, v51
	v_pk_mul_f32 v[48:49], v[66:67], v[48:49]
	s_cmp_gt_i32 s53, 0
	v_pk_mul_f32 v[48:49], v[62:63], v[48:49]
	v_pk_mul_f32 v[62:63], v[64:65], v[68:69]
	s_cselect_b32 s1, 0x80, 0
	v_pk_mul_f32 v[60:61], v[60:61], v[62:63]
	s_lshl_b32 s2, s12, 7
	v_cvt_pk_bf16_f32 v60, v60, v61
	v_mul_f32_e32 v61, 0xbfb8aa3b, v56
	v_exp_f32_e32 v62, v61
	v_mul_f32_e32 v61, 0xbfb8aa3b, v57
	v_exp_f32_e32 v63, v61
	v_cvt_pk_bf16_f32 v61, v48, v49
	v_add_f32_e32 v48, 1.0, v62
	v_mul_f32_e32 v62, 0xbfb8aa3b, v58
	v_add_f32_e32 v49, 1.0, v63
	v_exp_f32_e32 v62, v62
	v_mul_f32_e32 v63, 0xbfb8aa3b, v59
	v_exp_f32_e32 v63, v63
	v_rcp_f32_e32 v48, v48
	v_rcp_f32_e32 v49, v49
	v_add_f32_e32 v62, 1.0, v62
	v_rcp_f32_e32 v64, v62
	v_add_f32_e32 v62, 1.0, v63
	v_rcp_f32_e32 v65, v62
	v_pk_mul_f32 v[48:49], v[56:57], v[48:49]
	v_mul_f32_e32 v57, 0xbfb8aa3b, v44
	v_pk_mul_f32 v[48:49], v[52:53], v[48:49]
	s_or_b32 s2, s2, s56
	v_cvt_pk_bf16_f32 v62, v48, v49
	v_pk_mul_f32 v[48:49], v[58:59], v[64:65]
	v_exp_f32_e32 v58, v57
	v_pk_mul_f32 v[48:49], v[54:55], v[48:49]
	v_mul_f32_e32 v54, 0xbfb8aa3b, v47
	v_exp_f32_e32 v54, v54
	v_mul_f32_e32 v55, 0xbfb8aa3b, v46
	v_exp_f32_e32 v56, v55
	s_or_b32 s0, s1, s0
	v_add_f32_e32 v54, 1.0, v54
	v_rcp_f32_e32 v55, v54
	v_add_f32_e32 v54, 1.0, v56
	v_mul_f32_e32 v56, 0xbfb8aa3b, v45
	v_exp_f32_e32 v56, v56
	v_rcp_f32_e32 v54, v54
	v_or_b32_e32 v50, s2, v145
	v_add_u32_e32 v70, s0, v144
	v_add_f32_e32 v56, 1.0, v56
	v_rcp_f32_e32 v57, v56
	v_add_f32_e32 v56, 1.0, v58
	v_rcp_f32_e32 v56, v56
	v_pk_mul_f32 v[46:47], v[46:47], v[54:55]
	s_waitcnt vmcnt(14)
	v_ashrrev_i32_e32 v51, 31, v50
	v_pk_mul_f32 v[44:45], v[44:45], v[56:57]
	v_pk_mul_f32 v[42:43], v[42:43], v[46:47]
	v_pk_mul_f32 v[40:41], v[40:41], v[44:45]
	v_cvt_pk_bf16_f32 v63, v48, v49
	v_cvt_pk_bf16_f32 v40, v40, v41
	v_mul_f32_e32 v41, 0xbfb8aa3b, v36
	v_exp_f32_e32 v44, v41
	v_mul_f32_e32 v41, 0xbfb8aa3b, v37
	v_exp_f32_e32 v45, v41
	v_cvt_pk_bf16_f32 v41, v42, v43
	v_add_f32_e32 v42, 1.0, v44
	v_mul_f32_e32 v44, 0xbfb8aa3b, v38
	v_add_f32_e32 v43, 1.0, v45
	v_mul_f32_e32 v45, 0xbfb8aa3b, v39
	v_exp_f32_e32 v44, v44
	v_exp_f32_e32 v45, v45
	v_rcp_f32_e32 v42, v42
	v_rcp_f32_e32 v43, v43
	v_add_f32_e32 v44, 1.0, v44
	v_add_f32_e32 v45, 1.0, v45
	v_rcp_f32_e32 v44, v44
	v_rcp_f32_e32 v45, v45
	v_pk_mul_f32 v[36:37], v[36:37], v[42:43]
	s_movk_i32 s0, 0x1600
	v_pk_mul_f32 v[32:33], v[32:33], v[36:37]
	v_mul_f32_e32 v37, 0xbfb8aa3b, v28
	v_cvt_pk_bf16_f32 v42, v32, v33
	v_pk_mul_f32 v[32:33], v[38:39], v[44:45]
	v_exp_f32_e32 v38, v37
	v_pk_mul_f32 v[32:33], v[34:35], v[32:33]
	v_mul_f32_e32 v34, 0xbfb8aa3b, v31
	v_exp_f32_e32 v34, v34
	v_mul_f32_e32 v35, 0xbfb8aa3b, v30
	v_exp_f32_e32 v36, v35
	v_mov_b64_e32 v[48:49], s[10:11]
	v_add_f32_e32 v34, 1.0, v34
	v_rcp_f32_e32 v35, v34
	v_add_f32_e32 v34, 1.0, v36
	v_mul_f32_e32 v36, 0xbfb8aa3b, v29
	v_exp_f32_e32 v36, v36
	v_rcp_f32_e32 v34, v34
	v_cvt_pk_bf16_f32 v43, v32, v33
	v_or_b32_e32 v32, 16, v70
	v_add_f32_e32 v36, 1.0, v36
	v_rcp_f32_e32 v37, v36
	v_add_f32_e32 v36, 1.0, v38
	v_rcp_f32_e32 v36, v36
	v_pk_mul_f32 v[30:31], v[30:31], v[34:35]
	v_mad_i64_i32 v[52:53], s[2:3], v70, s0, v[48:49]
	v_pk_mul_f32 v[28:29], v[28:29], v[36:37]
	v_pk_mul_f32 v[26:27], v[26:27], v[30:31]
	v_pk_mul_f32 v[24:25], v[24:25], v[28:29]
	v_lshlrev_b64 v[50:51], 1, v[50:51]
	v_cvt_pk_bf16_f32 v24, v24, v25
	v_mul_f32_e32 v25, 0xbfb8aa3b, v20
	v_exp_f32_e32 v28, v25
	v_mul_f32_e32 v25, 0xbfb8aa3b, v21
	v_exp_f32_e32 v29, v25
	v_cvt_pk_bf16_f32 v25, v26, v27
	v_add_f32_e32 v26, 1.0, v28
	v_mul_f32_e32 v28, 0xbfb8aa3b, v22
	v_add_f32_e32 v27, 1.0, v29
	v_mul_f32_e32 v29, 0xbfb8aa3b, v23
	v_exp_f32_e32 v28, v28
	v_exp_f32_e32 v29, v29
	v_rcp_f32_e32 v26, v26
	v_rcp_f32_e32 v27, v27
	v_add_f32_e32 v28, 1.0, v28
	v_add_f32_e32 v29, 1.0, v29
	v_rcp_f32_e32 v28, v28
	v_rcp_f32_e32 v29, v29
	v_pk_mul_f32 v[20:21], v[20:21], v[26:27]
	v_mad_i64_i32 v[32:33], s[2:3], v32, s0, v[48:49]
	v_pk_mul_f32 v[16:17], v[16:17], v[20:21]
	v_mul_f32_e32 v21, 0xbfb8aa3b, v12
	v_cvt_pk_bf16_f32 v26, v16, v17
	v_pk_mul_f32 v[16:17], v[22:23], v[28:29]
	v_exp_f32_e32 v22, v21
	v_pk_mul_f32 v[16:17], v[18:19], v[16:17]
	v_mul_f32_e32 v18, 0xbfb8aa3b, v15
	v_exp_f32_e32 v18, v18
	v_mul_f32_e32 v19, 0xbfb8aa3b, v14
	v_exp_f32_e32 v20, v19
	v_cvt_pk_bf16_f32 v27, v16, v17
	v_add_f32_e32 v18, 1.0, v18
	v_rcp_f32_e32 v19, v18
	v_add_f32_e32 v18, 1.0, v20
	v_mul_f32_e32 v20, 0xbfb8aa3b, v13
	v_exp_f32_e32 v20, v20
	v_rcp_f32_e32 v18, v18
	v_or_b32_e32 v16, 32, v70
	v_mad_i64_i32 v[16:17], s[2:3], v16, s0, v[48:49]
	v_add_f32_e32 v20, 1.0, v20
	v_rcp_f32_e32 v21, v20
	v_add_f32_e32 v20, 1.0, v22
	v_rcp_f32_e32 v20, v20
	v_pk_mul_f32 v[14:15], v[14:15], v[18:19]
	v_lshl_add_u64 v[52:53], v[52:53], 0, v[50:51]
	v_pk_mul_f32 v[10:11], v[10:11], v[14:15]
	v_pk_mul_f32 v[12:13], v[12:13], v[20:21]
	v_lshl_add_u64 v[32:33], v[32:33], 0, v[50:51]
	v_pk_mul_f32 v[8:9], v[8:9], v[12:13]
	v_lshl_add_u64 v[16:17], v[16:17], 0, v[50:51]
	v_cvt_pk_bf16_f32 v8, v8, v9
	v_mul_f32_e32 v9, 0xbfb8aa3b, v4
	v_exp_f32_e32 v12, v9
	v_mul_f32_e32 v9, 0xbfb8aa3b, v5
	v_exp_f32_e32 v13, v9
	v_cvt_pk_bf16_f32 v9, v10, v11
	v_add_f32_e32 v10, 1.0, v12
	v_mul_f32_e32 v12, 0xbfb8aa3b, v6
	v_add_f32_e32 v11, 1.0, v13
	v_mul_f32_e32 v13, 0xbfb8aa3b, v7
	v_exp_f32_e32 v12, v12
	v_exp_f32_e32 v13, v13
	v_rcp_f32_e32 v10, v10
	v_rcp_f32_e32 v11, v11
	v_add_f32_e32 v12, 1.0, v12
	v_add_f32_e32 v13, 1.0, v13
	v_rcp_f32_e32 v12, v12
	v_rcp_f32_e32 v13, v13
	v_pk_mul_f32 v[4:5], v[4:5], v[10:11]
	global_store_dwordx4 v[52:53], v[60:63], off nt
	v_pk_mul_f32 v[0:1], v[0:1], v[4:5]
	global_store_dwordx4 v[32:33], v[40:43], off nt
	v_cvt_pk_bf16_f32 v10, v0, v1
	v_pk_mul_f32 v[0:1], v[6:7], v[12:13]
	global_store_dwordx4 v[16:17], v[24:27], off nt
	v_pk_mul_f32 v[0:1], v[2:3], v[0:1]
	s_nop 0
	v_cvt_pk_bf16_f32 v11, v0, v1
	v_or_b32_e32 v0, 48, v70
	v_mad_i64_i32 v[0:1], s[0:1], v0, s0, v[48:49]
	v_lshl_add_u64 v[0:1], v[0:1], 0, v[50:51]
	global_store_dwordx4 v[0:1], v[8:11], off nt

; __device__ __forceinline__ unsigned pk2(float lo, float hi) { f32x2 v = {lo, hi}; return __builtin_bit_cast(unsigned, __builtin_convertvector(v, bf16v2)); }
; __device__ __forceinline__ float sigmoidf_(float a) { return __builtin_amdgcn_rcpf(1.f + __expf(-a)); }
;   __device__ __forceinline__ void operator()(const Acc& acc, int brow, int bcol, int wr, int wc, int fr, int fq, int nai) const {
;     const int f0 = (bcol >> 1) + 32 * wc + 8 * fq;
;     asm volatile("s_waitcnt vmcnt(14)" ::: "memory");
; #pragma unroll
;     for (int ai = 0; ai < 2; ++ai)
; #pragma unroll
;       for (int m = 0; m < 4; ++m) if (ai < nai) {
;         const int r = brow + 128 * ai + 64 * wr + 16 * m + fr;
;         u32x4 o;
; #pragma unroll
;         for (int bj = 0; bj < 2; ++bj) {
;           const f32x4 a = acc[ai][bj][m][0], b = acc[ai][bj][m][1];
;           const float g0 = a[0] * sigmoidf_(a[0]) * b[0], g1 = a[1] * sigmoidf_(a[1]) * b[1];
;           const float g2 = a[2] * sigmoidf_(a[2]) * b[2], g3 = a[3] * sigmoidf_(a[3]) * b[3];
;           if (bj == 0) { o.x = pk2(g0, g1); o.y = pk2(g2, g3); } else { o.z = pk2(g0, g1); o.w = pk2(g2, g3); }
;         }
;         *(u32x4*)(G + (size_t)r * DFF + f0) = o;
;       }
.LBB0_2598:
	v_mul_f32_e32 v49, 0xbfb8aa3b, v67
	v_exp_f32_e32 v50, v49
	v_mul_f32_e32 v49, 0xbfb8aa3b, v66
	v_exp_f32_e32 v143, v49
	v_mul_f32_e32 v154, 0xbfb8aa3b, v64
	v_add_f32_e32 v50, 1.0, v50
	v_rcp_f32_e32 v51, v50
	v_add_f32_e32 v50, 1.0, v143
	v_mul_f32_e32 v143, 0xbfb8aa3b, v65
	v_exp_f32_e32 v143, v143
	v_exp_f32_e32 v154, v154
	v_rcp_f32_e32 v50, v50
	v_mul_f32_e32 v160, 0xbfb8aa3b, v47
	v_add_f32_e32 v143, 1.0, v143
	v_rcp_f32_e32 v155, v143
	v_add_f32_e32 v143, 1.0, v154
	v_rcp_f32_e32 v154, v143
	v_pk_mul_f32 v[50:51], v[66:67], v[50:51]
	v_exp_f32_e32 v160, v160
	v_pk_mul_f32 v[50:51], v[62:63], v[50:51]
	v_pk_mul_f32 v[154:155], v[64:65], v[154:155]
	v_mul_f32_e32 v161, 0xbfb8aa3b, v46
	v_pk_mul_f32 v[154:155], v[60:61], v[154:155]
	v_exp_f32_e32 v162, v161
	v_cvt_pk_bf16_f32 v154, v154, v155
	v_mul_f32_e32 v155, 0xbfb8aa3b, v56
	v_exp_f32_e32 v156, v155
	v_mul_f32_e32 v155, 0xbfb8aa3b, v57
	v_exp_f32_e32 v157, v155
	v_cvt_pk_bf16_f32 v155, v50, v51
	v_add_f32_e32 v50, 1.0, v156
	v_mul_f32_e32 v156, 0xbfb8aa3b, v58
	v_add_f32_e32 v51, 1.0, v157
	v_exp_f32_e32 v156, v156
	v_mul_f32_e32 v157, 0xbfb8aa3b, v59
	v_exp_f32_e32 v157, v157
	v_rcp_f32_e32 v50, v50
	v_rcp_f32_e32 v51, v51
	v_add_f32_e32 v156, 1.0, v156
	v_add_f32_e32 v160, 1.0, v160
	v_rcp_f32_e32 v158, v156
	v_add_f32_e32 v156, 1.0, v157
	v_rcp_f32_e32 v161, v160
	v_add_f32_e32 v160, 1.0, v162
	v_mul_f32_e32 v162, 0xbfb8aa3b, v45
	v_rcp_f32_e32 v159, v156
	v_exp_f32_e32 v162, v162
	v_mul_f32_e32 v163, 0xbfb8aa3b, v44
	v_exp_f32_e32 v164, v163
	v_pk_mul_f32 v[50:51], v[56:57], v[50:51]
	v_add_f32_e32 v162, 1.0, v162
	v_pk_mul_f32 v[50:51], v[52:53], v[50:51]
	v_lshl_or_b32 v142, s14, 7, v148
	v_cvt_pk_bf16_f32 v156, v50, v51
	v_pk_mul_f32 v[50:51], v[58:59], v[158:159]
	v_rcp_f32_e32 v160, v160
	v_pk_mul_f32 v[50:51], v[54:55], v[50:51]
	v_rcp_f32_e32 v163, v162
	v_add_f32_e32 v162, 1.0, v164
	v_lshl_add_u32 v49, s12, 8, v144
	v_ashrrev_i32_e32 v143, 31, v142
	v_cvt_pk_bf16_f32 v157, v50, v51
	v_mov_b64_e32 v[50:51], s[10:11]
	v_rcp_f32_e32 v162, v162
	v_mad_i64_i32 v[158:159], s[4:5], v49, s64, v[50:51]
	v_lshlrev_b64 v[142:143], 1, v[142:143]
	v_lshl_add_u64 v[158:159], v[158:159], 0, v[142:143]
	s_waitcnt vmcnt(14)
	global_store_dwordx4 v[158:159], v[154:157], off nt
	s_nop 1
	v_pk_mul_f32 v[154:155], v[46:47], v[160:161]
	v_mul_f32_e32 v160, 0xbfb8aa3b, v31
	v_pk_mul_f32 v[156:157], v[42:43], v[154:155]
	v_pk_mul_f32 v[154:155], v[44:45], v[162:163]
	v_exp_f32_e32 v160, v160
	v_pk_mul_f32 v[154:155], v[40:41], v[154:155]
	v_mul_f32_e32 v161, 0xbfb8aa3b, v30
	v_cvt_pk_bf16_f32 v154, v154, v155
	v_mul_f32_e32 v155, 0xbfb8aa3b, v36
	v_exp_f32_e32 v158, v155
	v_mul_f32_e32 v155, 0xbfb8aa3b, v37
	v_exp_f32_e32 v159, v155
	v_cvt_pk_bf16_f32 v155, v156, v157
	v_add_f32_e32 v156, 1.0, v158
	v_mul_f32_e32 v158, 0xbfb8aa3b, v38
	v_add_f32_e32 v157, 1.0, v159
	v_mul_f32_e32 v159, 0xbfb8aa3b, v39
	v_exp_f32_e32 v158, v158
	v_exp_f32_e32 v159, v159
	v_exp_f32_e32 v162, v161
	v_add_f32_e32 v160, 1.0, v160
	v_add_f32_e32 v158, 1.0, v158
	v_add_f32_e32 v159, 1.0, v159
	v_rcp_f32_e32 v161, v160
	v_add_f32_e32 v160, 1.0, v162
	v_mul_f32_e32 v162, 0xbfb8aa3b, v29
	v_rcp_f32_e32 v156, v156
	v_rcp_f32_e32 v157, v157
	v_rcp_f32_e32 v158, v158
	v_rcp_f32_e32 v159, v159
	v_exp_f32_e32 v162, v162
	v_mul_f32_e32 v163, 0xbfb8aa3b, v28
	v_exp_f32_e32 v164, v163
	v_pk_mul_f32 v[156:157], v[36:37], v[156:157]
	v_pk_mul_f32 v[158:159], v[38:39], v[158:159]
	v_add_f32_e32 v162, 1.0, v162
	v_pk_mul_f32 v[156:157], v[32:33], v[156:157]
	v_pk_mul_f32 v[158:159], v[34:35], v[158:159]
	v_rcp_f32_e32 v160, v160
	v_rcp_f32_e32 v163, v162
	v_add_f32_e32 v162, 1.0, v164
	v_cvt_pk_bf16_f32 v156, v156, v157
	v_cvt_pk_bf16_f32 v157, v158, v159
	v_or_b32_e32 v158, 16, v49
	v_rcp_f32_e32 v162, v162
	v_mad_i64_i32 v[158:159], s[4:5], v158, s64, v[50:51]
	v_lshl_add_u64 v[158:159], v[158:159], 0, v[142:143]
	global_store_dwordx4 v[158:159], v[154:157], off nt
	s_nop 1
	v_pk_mul_f32 v[154:155], v[30:31], v[160:161]
	v_mul_f32_e32 v160, 0xbfb8aa3b, v15
	v_pk_mul_f32 v[156:157], v[26:27], v[154:155]
	v_pk_mul_f32 v[154:155], v[28:29], v[162:163]
	v_exp_f32_e32 v160, v160
	v_pk_mul_f32 v[154:155], v[24:25], v[154:155]
	v_mul_f32_e32 v161, 0xbfb8aa3b, v14
	v_cvt_pk_bf16_f32 v154, v154, v155
	v_mul_f32_e32 v155, 0xbfb8aa3b, v20
	v_exp_f32_e32 v158, v155
	v_mul_f32_e32 v155, 0xbfb8aa3b, v21
	v_exp_f32_e32 v159, v155
	v_cvt_pk_bf16_f32 v155, v156, v157
	v_add_f32_e32 v156, 1.0, v158
	v_mul_f32_e32 v158, 0xbfb8aa3b, v22
	v_add_f32_e32 v157, 1.0, v159
	v_mul_f32_e32 v159, 0xbfb8aa3b, v23
	v_exp_f32_e32 v158, v158
	v_exp_f32_e32 v159, v159
	v_exp_f32_e32 v162, v161
	v_add_f32_e32 v160, 1.0, v160
	v_add_f32_e32 v158, 1.0, v158
	v_add_f32_e32 v159, 1.0, v159
	v_rcp_f32_e32 v161, v160
	v_add_f32_e32 v160, 1.0, v162
	v_mul_f32_e32 v162, 0xbfb8aa3b, v13
	v_rcp_f32_e32 v156, v156
	v_rcp_f32_e32 v157, v157
	v_rcp_f32_e32 v158, v158
	v_rcp_f32_e32 v159, v159
	v_exp_f32_e32 v162, v162
	v_mul_f32_e32 v163, 0xbfb8aa3b, v12
	v_exp_f32_e32 v164, v163
	v_pk_mul_f32 v[156:157], v[20:21], v[156:157]
	v_pk_mul_f32 v[158:159], v[22:23], v[158:159]
	v_add_f32_e32 v162, 1.0, v162
	v_pk_mul_f32 v[156:157], v[16:17], v[156:157]
	v_pk_mul_f32 v[158:159], v[18:19], v[158:159]
	v_rcp_f32_e32 v160, v160
	v_rcp_f32_e32 v163, v162
	v_add_f32_e32 v162, 1.0, v164
	v_cvt_pk_bf16_f32 v156, v156, v157
	v_cvt_pk_bf16_f32 v157, v158, v159
	v_or_b32_e32 v158, 32, v49
	v_rcp_f32_e32 v162, v162
	v_mad_i64_i32 v[158:159], s[4:5], v158, s64, v[50:51]
	v_lshl_add_u64 v[158:159], v[158:159], 0, v[142:143]
	global_store_dwordx4 v[158:159], v[154:157], off nt
; __device__ __forceinline__ unsigned pk2(float lo, float hi) { f32x2 v = {lo, hi}; return __builtin_bit_cast(unsigned, __builtin_convertvector(v, bf16v2)); }
; __device__ __forceinline__ float sigmoidf_(float a) { return __builtin_amdgcn_rcpf(1.f + __expf(-a)); }
;   __device__ __forceinline__ void operator()(const Acc& acc, int brow, int bcol, int wr, int wc, int fr, int fq, int nai) const {
;     const int f0 = (bcol >> 1) + 32 * wc + 8 * fq;
;     asm volatile("s_waitcnt vmcnt(14)" ::: "memory");
; #pragma unroll
;     for (int ai = 0; ai < 2; ++ai)
; #pragma unroll
;       for (int m = 0; m < 4; ++m) if (ai < nai) {
;         const int r = brow + 128 * ai + 64 * wr + 16 * m + fr;
;         u32x4 o;
; #pragma unroll
;         for (int bj = 0; bj < 2; ++bj) {
;           const f32x4 a = acc[ai][bj][m][0], b = acc[ai][bj][m][1];
;           const float g0 = a[0] * sigmoidf_(a[0]) * b[0], g1 = a[1] * sigmoidf_(a[1]) * b[1];
;           const float g2 = a[2] * sigmoidf_(a[2]) * b[2], g3 = a[3] * sigmoidf_(a[3]) * b[3];
;           if (bj == 0) { o.x = pk2(g0, g1); o.y = pk2(g2, g3); } else { o.z = pk2(g0, g1); o.w = pk2(g2, g3); }
;         }
;         *(u32x4*)(G + (size_t)r * DFF + f0) = o;
;       }
	s_nop 1
	v_pk_mul_f32 v[154:155], v[14:15], v[160:161]
	v_mul_f32_e32 v160, 0xbfb8aa3b, v131
	v_pk_mul_f32 v[156:157], v[10:11], v[154:155]
	v_pk_mul_f32 v[154:155], v[12:13], v[162:163]
	v_exp_f32_e32 v160, v160
	v_pk_mul_f32 v[154:155], v[8:9], v[154:155]
	v_mul_f32_e32 v161, 0xbfb8aa3b, v130
	v_cvt_pk_bf16_f32 v154, v154, v155
	v_mul_f32_e32 v155, 0xbfb8aa3b, v4
	v_exp_f32_e32 v158, v155
	v_mul_f32_e32 v155, 0xbfb8aa3b, v5
	v_exp_f32_e32 v159, v155
	v_cvt_pk_bf16_f32 v155, v156, v157
	v_add_f32_e32 v156, 1.0, v158
	v_mul_f32_e32 v158, 0xbfb8aa3b, v6
	v_add_f32_e32 v157, 1.0, v159
	v_mul_f32_e32 v159, 0xbfb8aa3b, v7
	v_exp_f32_e32 v158, v158
	v_exp_f32_e32 v159, v159
	v_rcp_f32_e32 v156, v156
	v_rcp_f32_e32 v157, v157
	v_add_f32_e32 v158, 1.0, v158
	v_add_f32_e32 v159, 1.0, v159
	v_rcp_f32_e32 v158, v158
	v_rcp_f32_e32 v159, v159
	v_pk_mul_f32 v[156:157], v[4:5], v[156:157]
	v_exp_f32_e32 v161, v161
	v_pk_mul_f32 v[156:157], v[0:1], v[156:157]
	v_pk_mul_f32 v[158:159], v[6:7], v[158:159]
	v_cvt_pk_bf16_f32 v156, v156, v157
	v_pk_mul_f32 v[158:159], v[2:3], v[158:159]
	v_mul_f32_e32 v163, 0xbfb8aa3b, v120
	v_cvt_pk_bf16_f32 v157, v158, v159
	v_or_b32_e32 v158, 48, v49
	v_mad_i64_i32 v[158:159], s[4:5], v158, s64, v[50:51]
	v_lshl_add_u64 v[158:159], v[158:159], 0, v[142:143]
	global_store_dwordx4 v[158:159], v[154:157], off nt
	v_exp_f32_e32 v164, v163
	s_nop 0
	v_mul_f32_e32 v156, 0xbfb8aa3b, v129
	v_exp_f32_e32 v156, v156
	v_mul_f32_e32 v157, 0xbfb8aa3b, v128
	v_exp_f32_e32 v158, v157
	v_add_f32_e32 v154, 1.0, v160
	v_rcp_f32_e32 v155, v154
	v_add_f32_e32 v154, 1.0, v161
	v_add_f32_e32 v156, 1.0, v156
	v_rcp_f32_e32 v154, v154
	v_rcp_f32_e32 v157, v156
	v_add_f32_e32 v156, 1.0, v158
	v_rcp_f32_e32 v156, v156
	v_pk_mul_f32 v[154:155], v[130:131], v[154:155]
	v_add_u32_e32 v160, 0x80, v49
	v_pk_mul_f32 v[158:159], v[126:127], v[154:155]
	v_pk_mul_f32 v[154:155], v[128:129], v[156:157]
	v_mul_f32_e32 v161, 0xbfb8aa3b, v122
	v_pk_mul_f32 v[154:155], v[124:125], v[154:155]
	v_exp_f32_e32 v162, v161
	v_cvt_pk_bf16_f32 v154, v154, v155
	v_mul_f32_e32 v155, 0xbfb8aa3b, v96
	v_exp_f32_e32 v156, v155
	v_mul_f32_e32 v155, 0xbfb8aa3b, v97
	v_exp_f32_e32 v157, v155
	v_cvt_pk_bf16_f32 v155, v158, v159
	v_mul_f32_e32 v158, 0xbfb8aa3b, v98
	v_mul_f32_e32 v159, 0xbfb8aa3b, v99
	v_exp_f32_e32 v158, v158
	v_exp_f32_e32 v159, v159
	v_add_f32_e32 v156, 1.0, v156
	v_add_f32_e32 v157, 1.0, v157
	v_add_f32_e32 v158, 1.0, v158
	v_add_f32_e32 v159, 1.0, v159
	v_rcp_f32_e32 v156, v156
	v_rcp_f32_e32 v157, v157
	v_rcp_f32_e32 v158, v158
	v_rcp_f32_e32 v159, v159
	v_pk_mul_f32 v[156:157], v[96:97], v[156:157]
	s_nop 0
	v_pk_mul_f32 v[156:157], v[92:93], v[156:157]
	v_pk_mul_f32 v[158:159], v[98:99], v[158:159]
	v_cvt_pk_bf16_f32 v156, v156, v157
	v_pk_mul_f32 v[158:159], v[94:95], v[158:159]
	s_nop 0
	v_cvt_pk_bf16_f32 v157, v158, v159
	v_mad_i64_i32 v[158:159], s[4:5], v160, s64, v[50:51]
	v_mul_f32_e32 v160, 0xbfb8aa3b, v123
	v_exp_f32_e32 v160, v160
	v_lshl_add_u64 v[158:159], v[158:159], 0, v[142:143]
	global_store_dwordx4 v[158:159], v[154:157], off nt
	v_add_f32_e32 v160, 1.0, v160
	v_rcp_f32_e32 v161, v160
	v_add_f32_e32 v160, 1.0, v162
	v_mul_f32_e32 v162, 0xbfb8aa3b, v121
	v_exp_f32_e32 v162, v162
	v_rcp_f32_e32 v160, v160
	v_add_f32_e32 v162, 1.0, v162
	v_rcp_f32_e32 v163, v162
	v_add_f32_e32 v162, 1.0, v164
	v_rcp_f32_e32 v162, v162
	v_pk_mul_f32 v[154:155], v[122:123], v[160:161]
	v_mul_f32_e32 v160, 0xbfb8aa3b, v115
	v_pk_mul_f32 v[156:157], v[118:119], v[154:155]
	v_pk_mul_f32 v[154:155], v[120:121], v[162:163]
	v_exp_f32_e32 v160, v160
	v_pk_mul_f32 v[154:155], v[116:117], v[154:155]
	v_mul_f32_e32 v161, 0xbfb8aa3b, v114
	v_cvt_pk_bf16_f32 v154, v154, v155
	v_mul_f32_e32 v155, 0xbfb8aa3b, v88
	v_exp_f32_e32 v158, v155
	v_mul_f32_e32 v155, 0xbfb8aa3b, v89
	v_exp_f32_e32 v159, v155
	v_cvt_pk_bf16_f32 v155, v156, v157
	v_add_f32_e32 v156, 1.0, v158
	v_mul_f32_e32 v158, 0xbfb8aa3b, v90
	v_add_f32_e32 v157, 1.0, v159
	v_mul_f32_e32 v159, 0xbfb8aa3b, v91
	v_exp_f32_e32 v158, v158
; __device__ __forceinline__ unsigned pk2(float lo, float hi) { f32x2 v = {lo, hi}; return __builtin_bit_cast(unsigned, __builtin_convertvector(v, bf16v2)); }
; __device__ __forceinline__ float sigmoidf_(float a) { return __builtin_amdgcn_rcpf(1.f + __expf(-a)); }
;   __device__ __forceinline__ void operator()(const Acc& acc, int brow, int bcol, int wr, int wc, int fr, int fq, int nai) const {
;     const int f0 = (bcol >> 1) + 32 * wc + 8 * fq;
;     asm volatile("s_waitcnt vmcnt(14)" ::: "memory");
; #pragma unroll
;     for (int ai = 0; ai < 2; ++ai)
; #pragma unroll
;       for (int m = 0; m < 4; ++m) if (ai < nai) {
;         const int r = brow + 128 * ai + 64 * wr + 16 * m + fr;
;         u32x4 o;
; #pragma unroll
;         for (int bj = 0; bj < 2; ++bj) {
;           const f32x4 a = acc[ai][bj][m][0], b = acc[ai][bj][m][1];
;           const float g0 = a[0] * sigmoidf_(a[0]) * b[0], g1 = a[1] * sigmoidf_(a[1]) * b[1];
;           const float g2 = a[2] * sigmoidf_(a[2]) * b[2], g3 = a[3] * sigmoidf_(a[3]) * b[3];
;           if (bj == 0) { o.x = pk2(g0, g1); o.y = pk2(g2, g3); } else { o.z = pk2(g0, g1); o.w = pk2(g2, g3); }
;         }
;         *(u32x4*)(G + (size_t)r * DFF + f0) = o;
;       }
	v_exp_f32_e32 v159, v159
	v_exp_f32_e32 v162, v161
	v_add_f32_e32 v160, 1.0, v160
	v_add_f32_e32 v158, 1.0, v158
	v_add_f32_e32 v159, 1.0, v159
	v_rcp_f32_e32 v161, v160
	v_add_f32_e32 v160, 1.0, v162
	v_mul_f32_e32 v162, 0xbfb8aa3b, v113
	v_rcp_f32_e32 v156, v156
	v_rcp_f32_e32 v157, v157
	v_rcp_f32_e32 v158, v158
	v_rcp_f32_e32 v159, v159
	v_exp_f32_e32 v162, v162
	v_mul_f32_e32 v163, 0xbfb8aa3b, v112
	v_exp_f32_e32 v164, v163
	v_pk_mul_f32 v[156:157], v[88:89], v[156:157]
	v_pk_mul_f32 v[158:159], v[90:91], v[158:159]
	v_add_f32_e32 v162, 1.0, v162
	v_pk_mul_f32 v[156:157], v[84:85], v[156:157]
	v_pk_mul_f32 v[158:159], v[86:87], v[158:159]
	v_rcp_f32_e32 v160, v160
	v_rcp_f32_e32 v163, v162
	v_add_f32_e32 v162, 1.0, v164
	v_cvt_pk_bf16_f32 v156, v156, v157
	v_cvt_pk_bf16_f32 v157, v158, v159
	v_add_u32_e32 v158, 0x90, v49
	v_rcp_f32_e32 v162, v162
	v_mad_i64_i32 v[158:159], s[4:5], v158, s64, v[50:51]
	v_lshl_add_u64 v[158:159], v[158:159], 0, v[142:143]
	global_store_dwordx4 v[158:159], v[154:157], off nt
	s_nop 1
	v_pk_mul_f32 v[154:155], v[114:115], v[160:161]
	v_mul_f32_e32 v160, 0xbfb8aa3b, v107
	v_pk_mul_f32 v[156:157], v[110:111], v[154:155]
	v_pk_mul_f32 v[154:155], v[112:113], v[162:163]
	v_exp_f32_e32 v160, v160
	v_pk_mul_f32 v[154:155], v[108:109], v[154:155]
	v_mul_f32_e32 v161, 0xbfb8aa3b, v106
	v_cvt_pk_bf16_f32 v154, v154, v155
	v_mul_f32_e32 v155, 0xbfb8aa3b, v80
	v_exp_f32_e32 v158, v155
	v_mul_f32_e32 v155, 0xbfb8aa3b, v81
	v_exp_f32_e32 v159, v155
	v_cvt_pk_bf16_f32 v155, v156, v157
	v_add_f32_e32 v156, 1.0, v158
	v_mul_f32_e32 v158, 0xbfb8aa3b, v82
	v_add_f32_e32 v157, 1.0, v159
	v_mul_f32_e32 v159, 0xbfb8aa3b, v83
	v_exp_f32_e32 v158, v158
	v_exp_f32_e32 v159, v159
	v_exp_f32_e32 v162, v161
	v_add_f32_e32 v160, 1.0, v160
	v_add_f32_e32 v158, 1.0, v158
	v_add_f32_e32 v159, 1.0, v159
	v_rcp_f32_e32 v161, v160
	v_add_f32_e32 v160, 1.0, v162
	v_mul_f32_e32 v162, 0xbfb8aa3b, v105
	v_rcp_f32_e32 v156, v156
	v_rcp_f32_e32 v157, v157
	v_rcp_f32_e32 v158, v158
	v_rcp_f32_e32 v159, v159
	v_exp_f32_e32 v162, v162
	v_mul_f32_e32 v163, 0xbfb8aa3b, v104
	v_exp_f32_e32 v164, v163
	v_pk_mul_f32 v[156:157], v[80:81], v[156:157]
	v_pk_mul_f32 v[158:159], v[82:83], v[158:159]
	v_add_f32_e32 v162, 1.0, v162
	v_pk_mul_f32 v[156:157], v[76:77], v[156:157]
	v_pk_mul_f32 v[158:159], v[78:79], v[158:159]
	v_rcp_f32_e32 v160, v160
	v_rcp_f32_e32 v163, v162
	v_add_f32_e32 v162, 1.0, v164
	v_cvt_pk_bf16_f32 v156, v156, v157
	v_cvt_pk_bf16_f32 v157, v158, v159
	v_add_u32_e32 v158, 0xa0, v49
	v_rcp_f32_e32 v162, v162
	v_mad_i64_i32 v[158:159], s[4:5], v158, s64, v[50:51]
	v_lshl_add_u64 v[158:159], v[158:159], 0, v[142:143]
	global_store_dwordx4 v[158:159], v[154:157], off nt
	v_add_u32_e32 v49, 0xb0, v49
	v_mad_i64_i32 v[50:51], s[4:5], v49, s64, v[50:51]
	v_pk_mul_f32 v[154:155], v[106:107], v[160:161]
	v_lshl_add_u64 v[50:51], v[50:51], 0, v[142:143]
	v_pk_mul_f32 v[156:157], v[102:103], v[154:155]
	v_pk_mul_f32 v[154:155], v[104:105], v[162:163]
	s_nop 0
	v_pk_mul_f32 v[154:155], v[100:101], v[154:155]
	s_nop 0
	v_cvt_pk_bf16_f32 v154, v154, v155
	v_mul_f32_e32 v155, 0xbfb8aa3b, v72
	v_exp_f32_e32 v158, v155
	v_mul_f32_e32 v155, 0xbfb8aa3b, v73
	v_exp_f32_e32 v159, v155
	v_cvt_pk_bf16_f32 v155, v156, v157
	v_add_f32_e32 v156, 1.0, v158
	v_mul_f32_e32 v158, 0xbfb8aa3b, v74
	v_add_f32_e32 v157, 1.0, v159
	v_mul_f32_e32 v159, 0xbfb8aa3b, v75
	v_exp_f32_e32 v158, v158
	v_exp_f32_e32 v159, v159
	v_rcp_f32_e32 v156, v156
	v_rcp_f32_e32 v157, v157
	v_add_f32_e32 v158, 1.0, v158
	v_add_f32_e32 v159, 1.0, v159
	v_rcp_f32_e32 v158, v158
	v_rcp_f32_e32 v159, v159
	v_pk_mul_f32 v[156:157], v[72:73], v[156:157]
	v_pk_mul_f32 v[158:159], v[74:75], v[158:159]
	v_pk_mul_f32 v[156:157], v[68:69], v[156:157]
	v_pk_mul_f32 v[158:159], v[70:71], v[158:159]
	v_cvt_pk_bf16_f32 v156, v156, v157
	v_cvt_pk_bf16_f32 v157, v158, v159
	global_store_dwordx4 v[50:51], v[154:157], off nt
	s_add_u32 s0, s0, 0xffffff00
	s_addc_u32 s1, s1, -1
	s_andn2_b64 vcc, exec, s[44:45]
	s_cbranch_vccnz .LBB0_2584

.LBB0_2603:
	s_add_u32 s0, s18, s8
	ds_read_b128 v[68:71], v149
	ds_read_b128 v[72:75], v149 offset:1024
	ds_read_b128 v[76:79], v149 offset:2048
	ds_read_b128 v[80:83], v149 offset:3072
	s_addc_u32 s1, s19, s9
	s_add_u32 s0, s0, 0x100
	s_addc_u32 s1, s1, 0
	s_add_u32 s4, s20, s8
	s_addc_u32 s5, s21, s9
	s_cmpk_eq_i32 s8, 0x700
	s_cselect_b32 s1, s19, s1
	s_cselect_b32 s0, s18, s0
	s_cselect_b32 s5, s43, s5
	s_cselect_b32 s4, s42, s4
	s_mov_b32 m0, s39
	v_lshl_add_u64 v[116:117], v[50:51], 0, s[8:9]
	ds_read_b128 v[84:87], v150
	ds_read_b128 v[88:91], v150 offset:1024
	ds_read_b128 v[92:95], v150 offset:2048
	ds_read_b128 v[96:99], v150 offset:3072
	ds_read_b128 v[100:103], v150 offset:4096
	ds_read_b128 v[104:107], v150 offset:5120
	ds_read_b128 v[108:111], v150 offset:6144
	ds_read_b128 v[112:115], v150 offset:7168
	global_load_lds_dwordx4 v[116:117], off
	v_lshl_add_u64 v[116:117], v[48:49], 0, s[8:9]
	s_mov_b32 m0, s41
	s_nop 0
	global_load_lds_dwordx4 v[116:117], off
	s_waitcnt lgkmcnt(8)
	s_barrier
	s_waitcnt lgkmcnt(0)
	s_setprio 1
	s_waitcnt lgkmcnt(0)
	v_mfma_f32_16x16x32_bf16 v[64:67], v[68:71], v[84:87], v[64:67]
	v_mfma_f32_16x16x32_bf16 v[60:63], v[76:79], v[84:87], v[60:63]
	v_mfma_f32_16x16x32_bf16 v[44:47], v[68:71], v[92:95], v[44:47]
	v_mfma_f32_16x16x32_bf16 v[40:43], v[76:79], v[92:95], v[40:43]
	v_mfma_f32_16x16x32_bf16 v[28:31], v[68:71], v[100:103], v[28:31]
	v_mfma_f32_16x16x32_bf16 v[24:27], v[76:79], v[100:103], v[24:27]
	v_mfma_f32_16x16x32_bf16 v[12:15], v[68:71], v[108:111], v[12:15]
	v_mfma_f32_16x16x32_bf16 v[8:11], v[76:79], v[108:111], v[8:11]
	v_mfma_f32_16x16x32_bf16 v[64:67], v[72:75], v[88:91], v[64:67]
	v_mfma_f32_16x16x32_bf16 v[60:63], v[80:83], v[88:91], v[60:63]
	v_mfma_f32_16x16x32_bf16 v[44:47], v[72:75], v[96:99], v[44:47]
	v_mfma_f32_16x16x32_bf16 v[40:43], v[80:83], v[96:99], v[40:43]
	v_mfma_f32_16x16x32_bf16 v[28:31], v[72:75], v[104:107], v[28:31]
	v_mfma_f32_16x16x32_bf16 v[24:27], v[80:83], v[104:107], v[24:27]
	v_mfma_f32_16x16x32_bf16 v[12:15], v[72:75], v[112:115], v[12:15]
	v_mfma_f32_16x16x32_bf16 v[8:11], v[80:83], v[112:115], v[8:11]
	s_setprio 0
	s_barrier
	s_mov_b32 m0, s66
	v_lshl_add_u64 v[116:117], s[4:5], 0, v[132:133]
	ds_read_b128 v[68:71], v151
	ds_read_b128 v[72:75], v151 offset:1024
	ds_read_b128 v[76:79], v151 offset:2048
	ds_read_b128 v[80:83], v151 offset:3072
	global_load_lds_dwordx4 v[116:117], off
	v_lshl_add_u64 v[118:119], s[4:5], 0, v[134:135]
	s_mov_b32 m0, s67
	s_nop 0
	global_load_lds_dwordx4 v[118:119], off
	s_barrier
	s_waitcnt lgkmcnt(0)
	s_setprio 1
	s_waitcnt lgkmcnt(0)
	v_mfma_f32_16x16x32_bf16 v[56:59], v[68:71], v[84:87], v[56:59]
	v_mfma_f32_16x16x32_bf16 v[52:55], v[76:79], v[84:87], v[52:55]
	v_mfma_f32_16x16x32_bf16 v[36:39], v[68:71], v[92:95], v[36:39]
	v_mfma_f32_16x16x32_bf16 v[32:35], v[76:79], v[92:95], v[32:35]
	v_mfma_f32_16x16x32_bf16 v[20:23], v[68:71], v[100:103], v[20:23]
	v_mfma_f32_16x16x32_bf16 v[16:19], v[76:79], v[100:103], v[16:19]
	v_mfma_f32_16x16x32_bf16 v[4:7], v[68:71], v[108:111], v[4:7]
	v_mfma_f32_16x16x32_bf16 v[0:3], v[76:79], v[108:111], v[0:3]
	v_mfma_f32_16x16x32_bf16 v[56:59], v[72:75], v[88:91], v[56:59]
	v_mfma_f32_16x16x32_bf16 v[52:55], v[80:83], v[88:91], v[52:55]
	v_mfma_f32_16x16x32_bf16 v[36:39], v[72:75], v[96:99], v[36:39]
	v_mfma_f32_16x16x32_bf16 v[32:35], v[80:83], v[96:99], v[32:35]
	v_mfma_f32_16x16x32_bf16 v[20:23], v[72:75], v[104:107], v[20:23]
	v_mfma_f32_16x16x32_bf16 v[16:19], v[80:83], v[104:107], v[16:19]
	v_mfma_f32_16x16x32_bf16 v[4:7], v[72:75], v[112:115], v[4:7]
	v_mfma_f32_16x16x32_bf16 v[0:3], v[80:83], v[112:115], v[0:3]
	s_setprio 0
	s_mov_b32 m0, s13
	v_lshl_add_u64 v[120:121], s[0:1], 0, v[132:133]
	s_barrier
	global_load_lds_dwordx4 v[120:121], off
	v_lshl_add_u64 v[122:123], s[0:1], 0, v[134:135]
	s_mov_b32 m0, s15
	s_nop 0
	global_load_lds_dwordx4 v[122:123], off
	s_barrier
	s_waitcnt lgkmcnt(0)
	s_barrier
	s_add_u32 s26, s4, 0x40000
	s_addc_u32 s27, s5, 0
	s_mov_b32 m0, s70
	v_lshl_add_u64 v[68:69], s[26:27], 0, v[132:133]
	global_load_lds_dwordx4 v[68:69], off
	v_lshl_add_u64 v[68:69], s[26:27], 0, v[134:135]
	s_mov_b32 m0, s71
	s_nop 0
	global_load_lds_dwordx4 v[68:69], off
	s_waitcnt vmcnt(6)
	s_barrier
	s_barrier
	ds_read_b128 v[68:71], v152
	ds_read_b128 v[72:75], v152 offset:1024
	ds_read_b128 v[76:79], v152 offset:2048
	ds_read_b128 v[80:83], v152 offset:3072
	s_add_u32 s0, s0, s24
	s_addc_u32 s1, s1, s25
	s_mov_b32 m0, s23
	v_lshl_add_u64 v[124:125], s[0:1], 0, v[132:133]
	ds_read_b128 v[84:87], v150 offset:32768
	ds_read_b128 v[88:91], v150 offset:33792
	ds_read_b128 v[92:95], v150 offset:34816
	ds_read_b128 v[96:99], v150 offset:35840
	ds_read_b128 v[100:103], v150 offset:36864
	ds_read_b128 v[104:107], v150 offset:37888
	ds_read_b128 v[108:111], v150 offset:38912
	ds_read_b128 v[112:115], v150 offset:39936
	global_load_lds_dwordx4 v[124:125], off
	v_lshl_add_u64 v[124:125], s[0:1], 0, v[134:135]
	s_mov_b32 m0, s54
	s_nop 0
	global_load_lds_dwordx4 v[124:125], off
	s_waitcnt lgkmcnt(8)
	s_barrier
	s_waitcnt lgkmcnt(0)
	s_setprio 1
	s_waitcnt lgkmcnt(0)
	v_mfma_f32_16x16x32_bf16 v[64:67], v[68:71], v[84:87], v[64:67]
	v_mfma_f32_16x16x32_bf16 v[60:63], v[76:79], v[84:87], v[60:63]
	v_mfma_f32_16x16x32_bf16 v[44:47], v[68:71], v[92:95], v[44:47]
	v_mfma_f32_16x16x32_bf16 v[40:43], v[76:79], v[92:95], v[40:43]
	v_mfma_f32_16x16x32_bf16 v[28:31], v[68:71], v[100:103], v[28:31]
	v_mfma_f32_16x16x32_bf16 v[24:27], v[76:79], v[100:103], v[24:27]
	v_mfma_f32_16x16x32_bf16 v[12:15], v[68:71], v[108:111], v[12:15]
	v_mfma_f32_16x16x32_bf16 v[8:11], v[76:79], v[108:111], v[8:11]
	v_mfma_f32_16x16x32_bf16 v[64:67], v[72:75], v[88:91], v[64:67]
	v_mfma_f32_16x16x32_bf16 v[60:63], v[80:83], v[88:91], v[60:63]
	v_mfma_f32_16x16x32_bf16 v[44:47], v[72:75], v[96:99], v[44:47]
	v_mfma_f32_16x16x32_bf16 v[40:43], v[80:83], v[96:99], v[40:43]
	v_mfma_f32_16x16x32_bf16 v[28:31], v[72:75], v[104:107], v[28:31]
	v_mfma_f32_16x16x32_bf16 v[24:27], v[80:83], v[104:107], v[24:27]
	v_mfma_f32_16x16x32_bf16 v[12:15], v[72:75], v[112:115], v[12:15]
	v_mfma_f32_16x16x32_bf16 v[8:11], v[80:83], v[112:115], v[8:11]
	s_setprio 0
	s_barrier
	s_mov_b32 m0, s2
	v_lshl_add_u64 v[116:117], v[116:117], 0, s[16:17]
	ds_read_b128 v[68:71], v153
	ds_read_b128 v[72:75], v153 offset:1024
	ds_read_b128 v[76:79], v153 offset:2048
	ds_read_b128 v[80:83], v153 offset:3072
	global_load_lds_dwordx4 v[116:117], off
	v_lshl_add_u64 v[116:117], v[118:119], 0, s[16:17]
	s_mov_b32 m0, s3
	s_nop 0
	global_load_lds_dwordx4 v[116:117], off
	s_barrier
	s_waitcnt lgkmcnt(0)
	s_setprio 1
	s_waitcnt lgkmcnt(0)
	v_mfma_f32_16x16x32_bf16 v[56:59], v[68:71], v[84:87], v[56:59]
	v_mfma_f32_16x16x32_bf16 v[52:55], v[76:79], v[84:87], v[52:55]
	v_mfma_f32_16x16x32_bf16 v[36:39], v[68:71], v[92:95], v[36:39]
	v_mfma_f32_16x16x32_bf16 v[32:35], v[76:79], v[92:95], v[32:35]
	v_mfma_f32_16x16x32_bf16 v[20:23], v[68:71], v[100:103], v[20:23]
	v_mfma_f32_16x16x32_bf16 v[16:19], v[76:79], v[100:103], v[16:19]
	v_mfma_f32_16x16x32_bf16 v[4:7], v[68:71], v[108:111], v[4:7]
	v_mfma_f32_16x16x32_bf16 v[0:3], v[76:79], v[108:111], v[0:3]
	v_mfma_f32_16x16x32_bf16 v[56:59], v[72:75], v[88:91], v[56:59]
	v_mfma_f32_16x16x32_bf16 v[52:55], v[80:83], v[88:91], v[52:55]
	v_mfma_f32_16x16x32_bf16 v[36:39], v[72:75], v[96:99], v[36:39]
	v_mfma_f32_16x16x32_bf16 v[32:35], v[80:83], v[96:99], v[32:35]
	v_mfma_f32_16x16x32_bf16 v[20:23], v[72:75], v[104:107], v[20:23]
	v_mfma_f32_16x16x32_bf16 v[16:19], v[80:83], v[104:107], v[16:19]
	v_mfma_f32_16x16x32_bf16 v[4:7], v[72:75], v[112:115], v[4:7]
	v_mfma_f32_16x16x32_bf16 v[0:3], v[80:83], v[112:115], v[0:3]
	s_setprio 0
	s_mov_b32 m0, s57
	v_lshl_add_u64 v[68:69], v[120:121], 0, s[16:17]
	s_barrier
	global_load_lds_dwordx4 v[68:69], off
	v_lshl_add_u64 v[68:69], v[122:123], 0, s[16:17]
	s_mov_b32 m0, s58
	s_nop 0
	global_load_lds_dwordx4 v[68:69], off
	s_barrier
	s_waitcnt lgkmcnt(0)
	s_barrier
	s_add_u32 s0, s4, 0x40080
	s_addc_u32 s1, s5, 0
	s_mov_b32 m0, s50
	v_lshl_add_u64 v[68:69], s[0:1], 0, v[132:133]
	global_load_lds_dwordx4 v[68:69], off
	v_lshl_add_u64 v[68:69], s[0:1], 0, v[134:135]
	s_mov_b32 m0, s51
	s_add_i32 s22, s22, 2
	global_load_lds_dwordx4 v[68:69], off
	s_waitcnt vmcnt(6)
	s_add_u32 s8, s8, 0x100
	s_addc_u32 s9, s9, 0
	s_cmp_gt_u32 s22, 13
	s_barrier
	s_barrier
	s_cbranch_scc0 .LBB0_2603
; __device__ __forceinline__ unsigned pk2(float lo, float hi) { f32x2 v = {lo, hi}; return __builtin_bit_cast(unsigned, __builtin_convertvector(v, bf16v2)); }
; __device__ __forceinline__ float sigmoidf_(float a) { return __builtin_amdgcn_rcpf(1.f + __expf(-a)); }
;     ...
;       epi(acc, cpm * BM + (chf > 0 ? HALF : 0), cpn * BM, wr, wc, fr, fq, 1);
;   __device__ __forceinline__ void operator()(const Acc& acc, int brow, int bcol, int wr, int wc, int fr, int fq, int nai) const {
;     const int f0 = (bcol >> 1) + 32 * wc + 8 * fq;
;     asm volatile("s_waitcnt vmcnt(14)" ::: "memory");
; #pragma unroll
;     for (int ai = 0; ai < 2; ++ai)
; #pragma unroll
;       for (int m = 0; m < 4; ++m) if (ai < nai) {
;         const int r = brow + 128 * ai + 64 * wr + 16 * m + fr;
;         u32x4 o;
; #pragma unroll
;         for (int bj = 0; bj < 2; ++bj) {
;           const f32x4 a = acc[ai][bj][m][0], b = acc[ai][bj][m][1];
;           const float g0 = a[0] * sigmoidf_(a[0]) * b[0], g1 = a[1] * sigmoidf_(a[1]) * b[1];
;           const float g2 = a[2] * sigmoidf_(a[2]) * b[2], g3 = a[3] * sigmoidf_(a[3]) * b[3];
;           if (bj == 0) { o.x = pk2(g0, g1); o.y = pk2(g2, g3); } else { o.z = pk2(g0, g1); o.w = pk2(g2, g3); }
;         }
;         *(u32x4*)(G + (size_t)r * DFF + f0) = o;
;       }
	v_mul_f32_e32 v48, 0xbfb8aa3b, v67
	v_exp_f32_e32 v48, v48
	v_mul_f32_e32 v49, 0xbfb8aa3b, v66
	v_exp_f32_e32 v51, v49
	v_mul_f32_e32 v68, 0xbfb8aa3b, v64
	v_add_f32_e32 v48, 1.0, v48
	v_rcp_f32_e32 v49, v48
	v_add_f32_e32 v48, 1.0, v51
	v_mul_f32_e32 v51, 0xbfb8aa3b, v65
	v_exp_f32_e32 v51, v51
	v_exp_f32_e32 v68, v68
	v_rcp_f32_e32 v48, v48
	s_lshl_b32 s0, s12, 8
	v_add_f32_e32 v51, 1.0, v51
	v_rcp_f32_e32 v69, v51
	v_add_f32_e32 v51, 1.0, v68
	v_rcp_f32_e32 v68, v51
	v_pk_mul_f32 v[48:49], v[66:67], v[48:49]
	s_cmp_gt_i32 s53, 0
	v_pk_mul_f32 v[48:49], v[62:63], v[48:49]
	v_pk_mul_f32 v[62:63], v[64:65], v[68:69]
	s_cselect_b32 s1, 0x80, 0
	v_pk_mul_f32 v[60:61], v[60:61], v[62:63]
	s_lshl_b32 s2, s14, 7
	v_cvt_pk_bf16_f32 v60, v60, v61
	v_mul_f32_e32 v61, 0xbfb8aa3b, v56
	v_exp_f32_e32 v62, v61
	v_mul_f32_e32 v61, 0xbfb8aa3b, v57
	v_exp_f32_e32 v63, v61
	v_cvt_pk_bf16_f32 v61, v48, v49
	v_add_f32_e32 v48, 1.0, v62
	v_mul_f32_e32 v62, 0xbfb8aa3b, v58
	v_add_f32_e32 v49, 1.0, v63
	v_exp_f32_e32 v62, v62
	v_mul_f32_e32 v63, 0xbfb8aa3b, v59
	v_exp_f32_e32 v63, v63
	v_rcp_f32_e32 v48, v48
	v_rcp_f32_e32 v49, v49
	v_add_f32_e32 v62, 1.0, v62
	v_rcp_f32_e32 v64, v62
	v_add_f32_e32 v62, 1.0, v63
	v_rcp_f32_e32 v65, v62
	v_pk_mul_f32 v[48:49], v[56:57], v[48:49]
	v_mul_f32_e32 v57, 0xbfb8aa3b, v44
	v_pk_mul_f32 v[48:49], v[52:53], v[48:49]
	s_or_b32 s2, s2, s55
	v_cvt_pk_bf16_f32 v62, v48, v49
	v_pk_mul_f32 v[48:49], v[58:59], v[64:65]
	v_exp_f32_e32 v58, v57
	v_pk_mul_f32 v[48:49], v[54:55], v[48:49]
	v_mul_f32_e32 v54, 0xbfb8aa3b, v47
	v_exp_f32_e32 v54, v54
	v_mul_f32_e32 v55, 0xbfb8aa3b, v46
	v_exp_f32_e32 v56, v55
	s_or_b32 s0, s1, s0
	v_add_f32_e32 v54, 1.0, v54
	v_rcp_f32_e32 v55, v54
	v_add_f32_e32 v54, 1.0, v56
	v_mul_f32_e32 v56, 0xbfb8aa3b, v45
	v_exp_f32_e32 v56, v56
	v_rcp_f32_e32 v54, v54
	v_or_b32_e32 v50, s2, v145
	v_add_u32_e32 v70, s0, v144
	v_add_f32_e32 v56, 1.0, v56
	v_rcp_f32_e32 v57, v56
	v_add_f32_e32 v56, 1.0, v58
	v_rcp_f32_e32 v56, v56
	v_pk_mul_f32 v[46:47], v[46:47], v[54:55]
	s_waitcnt vmcnt(14)
	v_ashrrev_i32_e32 v51, 31, v50
	v_pk_mul_f32 v[44:45], v[44:45], v[56:57]
	v_pk_mul_f32 v[42:43], v[42:43], v[46:47]
	v_pk_mul_f32 v[40:41], v[40:41], v[44:45]
	v_cvt_pk_bf16_f32 v63, v48, v49
	v_cvt_pk_bf16_f32 v40, v40, v41
	v_mul_f32_e32 v41, 0xbfb8aa3b, v36
	v_exp_f32_e32 v44, v41
	v_mul_f32_e32 v41, 0xbfb8aa3b, v37
	v_exp_f32_e32 v45, v41
	v_cvt_pk_bf16_f32 v41, v42, v43
	v_add_f32_e32 v42, 1.0, v44
	v_mul_f32_e32 v44, 0xbfb8aa3b, v38
	v_add_f32_e32 v43, 1.0, v45
	v_mul_f32_e32 v45, 0xbfb8aa3b, v39
	v_exp_f32_e32 v44, v44
	v_exp_f32_e32 v45, v45
	v_rcp_f32_e32 v42, v42
	v_rcp_f32_e32 v43, v43
	v_add_f32_e32 v44, 1.0, v44
	v_add_f32_e32 v45, 1.0, v45
	v_rcp_f32_e32 v44, v44
	v_rcp_f32_e32 v45, v45
	v_pk_mul_f32 v[36:37], v[36:37], v[42:43]
	s_movk_i32 s0, 0x1600
	v_pk_mul_f32 v[32:33], v[32:33], v[36:37]
	v_mul_f32_e32 v37, 0xbfb8aa3b, v28
	v_cvt_pk_bf16_f32 v42, v32, v33
	v_pk_mul_f32 v[32:33], v[38:39], v[44:45]
	v_exp_f32_e32 v38, v37
	v_pk_mul_f32 v[32:33], v[34:35], v[32:33]
	v_mul_f32_e32 v34, 0xbfb8aa3b, v31
	v_exp_f32_e32 v34, v34
	v_mul_f32_e32 v35, 0xbfb8aa3b, v30
	v_exp_f32_e32 v36, v35
	v_mov_b64_e32 v[48:49], s[10:11]
	v_add_f32_e32 v34, 1.0, v34
	v_rcp_f32_e32 v35, v34
	v_add_f32_e32 v34, 1.0, v36
	v_mul_f32_e32 v36, 0xbfb8aa3b, v29
	v_exp_f32_e32 v36, v36
	v_rcp_f32_e32 v34, v34
	v_cvt_pk_bf16_f32 v43, v32, v33
	v_or_b32_e32 v32, 16, v70
	v_add_f32_e32 v36, 1.0, v36
	v_rcp_f32_e32 v37, v36
	v_add_f32_e32 v36, 1.0, v38
	v_rcp_f32_e32 v36, v36
	v_pk_mul_f32 v[30:31], v[30:31], v[34:35]
	v_mad_i64_i32 v[52:53], s[2:3], v70, s0, v[48:49]
	v_pk_mul_f32 v[28:29], v[28:29], v[36:37]
	v_pk_mul_f32 v[26:27], v[26:27], v[30:31]
	v_pk_mul_f32 v[24:25], v[24:25], v[28:29]
	v_lshlrev_b64 v[50:51], 1, v[50:51]
	v_cvt_pk_bf16_f32 v24, v24, v25
	v_mul_f32_e32 v25, 0xbfb8aa3b, v20
	v_exp_f32_e32 v28, v25
	v_mul_f32_e32 v25, 0xbfb8aa3b, v21
	v_exp_f32_e32 v29, v25
	v_cvt_pk_bf16_f32 v25, v26, v27
	v_add_f32_e32 v26, 1.0, v28
	v_mul_f32_e32 v28, 0xbfb8aa3b, v22
	v_add_f32_e32 v27, 1.0, v29
	v_mul_f32_e32 v29, 0xbfb8aa3b, v23
	v_exp_f32_e32 v28, v28
	v_exp_f32_e32 v29, v29
	v_rcp_f32_e32 v26, v26
	v_rcp_f32_e32 v27, v27
	v_add_f32_e32 v28, 1.0, v28
	v_add_f32_e32 v29, 1.0, v29
	v_rcp_f32_e32 v28, v28
	v_rcp_f32_e32 v29, v29
	v_pk_mul_f32 v[20:21], v[20:21], v[26:27]
	v_mad_i64_i32 v[32:33], s[2:3], v32, s0, v[48:49]
	v_pk_mul_f32 v[16:17], v[16:17], v[20:21]
	v_mul_f32_e32 v21, 0xbfb8aa3b, v12
	v_cvt_pk_bf16_f32 v26, v16, v17
	v_pk_mul_f32 v[16:17], v[22:23], v[28:29]
	v_exp_f32_e32 v22, v21
	v_pk_mul_f32 v[16:17], v[18:19], v[16:17]
	v_mul_f32_e32 v18, 0xbfb8aa3b, v15
	v_exp_f32_e32 v18, v18
	v_mul_f32_e32 v19, 0xbfb8aa3b, v14
	v_exp_f32_e32 v20, v19
	v_cvt_pk_bf16_f32 v27, v16, v17
	v_add_f32_e32 v18, 1.0, v18
	v_rcp_f32_e32 v19, v18
	v_add_f32_e32 v18, 1.0, v20
	v_mul_f32_e32 v20, 0xbfb8aa3b, v13
	v_exp_f32_e32 v20, v20
	v_rcp_f32_e32 v18, v18
	v_or_b32_e32 v16, 32, v70
	v_mad_i64_i32 v[16:17], s[2:3], v16, s0, v[48:49]
	v_add_f32_e32 v20, 1.0, v20
	v_rcp_f32_e32 v21, v20
	v_add_f32_e32 v20, 1.0, v22
	v_rcp_f32_e32 v20, v20
	v_pk_mul_f32 v[14:15], v[14:15], v[18:19]
	v_lshl_add_u64 v[52:53], v[52:53], 0, v[50:51]
	v_pk_mul_f32 v[10:11], v[10:11], v[14:15]
	v_pk_mul_f32 v[12:13], v[12:13], v[20:21]
	v_lshl_add_u64 v[32:33], v[32:33], 0, v[50:51]
	v_pk_mul_f32 v[8:9], v[8:9], v[12:13]
	v_lshl_add_u64 v[16:17], v[16:17], 0, v[50:51]
	v_cvt_pk_bf16_f32 v8, v8, v9
	v_mul_f32_e32 v9, 0xbfb8aa3b, v4
	v_exp_f32_e32 v12, v9
	v_mul_f32_e32 v9, 0xbfb8aa3b, v5
	v_exp_f32_e32 v13, v9
	v_cvt_pk_bf16_f32 v9, v10, v11
	v_add_f32_e32 v10, 1.0, v12
	v_mul_f32_e32 v12, 0xbfb8aa3b, v6
	v_add_f32_e32 v11, 1.0, v13
	v_mul_f32_e32 v13, 0xbfb8aa3b, v7
	v_exp_f32_e32 v12, v12
	v_exp_f32_e32 v13, v13
	v_rcp_f32_e32 v10, v10
	v_rcp_f32_e32 v11, v11
	v_add_f32_e32 v12, 1.0, v12
	v_add_f32_e32 v13, 1.0, v13
	v_rcp_f32_e32 v12, v12
	v_rcp_f32_e32 v13, v13
	v_pk_mul_f32 v[4:5], v[4:5], v[10:11]
	global_store_dwordx4 v[52:53], v[60:63], off nt
	v_pk_mul_f32 v[0:1], v[0:1], v[4:5]
	global_store_dwordx4 v[32:33], v[40:43], off nt
	v_cvt_pk_bf16_f32 v10, v0, v1
	v_pk_mul_f32 v[0:1], v[6:7], v[12:13]
	global_store_dwordx4 v[16:17], v[24:27], off nt
	v_pk_mul_f32 v[0:1], v[2:3], v[0:1]
	s_nop 0
	v_cvt_pk_bf16_f32 v11, v0, v1
	v_or_b32_e32 v0, 48, v70
	v_mad_i64_i32 v[0:1], s[0:1], v0, s0, v[48:49]
	v_lshl_add_u64 v[0:1], v[0:1], 0, v[50:51]
	global_store_dwordx4 v[0:1], v[8:11], off nt
